# gMLP V row loads marked nt (single-use data: keep the attention operands in the memory-side cache)
# baseline (speedup 1.0000x reference)
.LBB0_124:
	s_ashr_i32 s14, s16, 9
	s_ashr_i32 s15, s14, 31
	s_lshl_b64 s[14:15], s[14:15], 12
	s_and_b32 s19, s18, 0xf80
	s_or_b32 s14, s14, s19
	v_mov_b32_e32 v1, s15
	v_or_b32_e32 v0, s14, v156
	s_and_b32 s20, s17, 0x3c0
	v_lshlrev_b64 v[2:3], 7, v[0:1]
	v_lshlrev_b64 v[0:1], 11, v[0:1]
	v_lshl_add_u64 v[0:1], s[28:29], 0, v[0:1]
	s_lshl_b32 s78, s20, 1
	v_lshl_add_u64 v[2:3], s[0:1], 0, v[2:3]
	v_lshl_add_u64 v[28:29], v[0:1], 0, s[78:79]
	s_lshl_b32 s100, s83, 4
	v_lshrrev_b32_e32 v76, 3, v244
	v_add_u32_e32 v76, s100, v76
	s_add_i32 s100, s100, s14
	s_lshl_b32 s100, s100, 7
	s_add_u32 s100, s0, s100
	s_addc_u32 s101, s1, 0
	v_lshlrev_b32_e32 v60, 4, v244
	global_load_dwordx4 v[56:59], v60, s[100:101]
	global_load_dwordx4 v[64:67], v60, s[100:101] offset:1024
	s_lshl_b32 s100, s14, 11
	s_add_u32 s100, s100, s28
	s_addc_u32 s101, s29, 0
	s_add_u32 s100, s100, s78
	s_addc_u32 s101, s101, s79
	s_mul_i32 s32, s83, 0x4400
	v_lshrrev_b32_e32 v105, 3, v244
	v_and_b32_e32 v106, 7, v244
	v_lshlrev_b32_e32 v105, 11, v105
	v_lshl_add_u32 v105, v106, 4, v105
	v_mul_u32_u24_e32 v104, 0x110, v244
	v_add_u32_e32 v104, s32, v104
	v_lshrrev_b32_e32 v107, 4, v244
	v_mul_u32_u24_e32 v107, 0x110, v107
	v_bfe_u32 v108, v244, 3, 1
	v_lshl_add_u32 v107, v108, 7, v107
	v_lshl_add_u32 v107, v106, 4, v107
	v_add_u32_e32 v107, s32, v107
	global_load_dwordx4 v[120:123], v105, s[100:101] nt
	v_add_u32_e32 v105, 0x4000, v105
	global_load_dwordx4 v[48:51], v105, s[100:101] nt
	v_add_u32_e32 v105, 0x4000, v105
	global_load_dwordx4 v[40:43], v105, s[100:101] nt
	v_add_u32_e32 v105, 0x4000, v105
	global_load_dwordx4 v[32:35], v105, s[100:101] nt
	v_add_u32_e32 v105, 0x4000, v105
	global_load_dwordx4 v[24:27], v105, s[100:101] nt
	v_add_u32_e32 v105, 0x4000, v105
	global_load_dwordx4 v[16:19], v105, s[100:101] nt
	v_add_u32_e32 v105, 0x4000, v105
	global_load_dwordx4 v[8:11], v105, s[100:101] nt
	v_add_u32_e32 v105, 0x4000, v105
	global_load_dwordx4 v[0:3], v105, s[100:101] nt
	v_add_u32_e32 v105, 0x4000, v105
	global_load_dwordx4 v[124:127], v105, s[100:101] nt
	v_add_u32_e32 v105, 0x4000, v105
	global_load_dwordx4 v[52:55], v105, s[100:101] nt
	v_add_u32_e32 v105, 0x4000, v105
	global_load_dwordx4 v[44:47], v105, s[100:101] nt
	v_add_u32_e32 v105, 0x4000, v105
	global_load_dwordx4 v[36:39], v105, s[100:101] nt
	v_add_u32_e32 v105, 0x4000, v105
	global_load_dwordx4 v[28:31], v105, s[100:101] nt
	v_add_u32_e32 v105, 0x4000, v105
	global_load_dwordx4 v[20:23], v105, s[100:101] nt
	v_add_u32_e32 v105, 0x4000, v105
	global_load_dwordx4 v[12:15], v105, s[100:101] nt
	v_add_u32_e32 v105, 0x4000, v105
	global_load_dwordx4 v[4:7], v105, s[100:101] nt
	s_lshl_b32 s22, s20, 2
	s_add_i32 s22, s22, 0
	s_add_i32 s24, s22, 0x22000
	s_add_i32 s22, s22, 0x23000
	s_and_b32 s19, s17, 0x380
	v_add_u32_e32 v175, v165, v169
	v_mov_b32_e32 v155, s15
	v_or_b32_e32 v154, s14, v164
	v_add_u32_e32 v177, v165, v171
	v_mov_b32_e32 v151, s15
	v_or_b32_e32 v150, s14, v166
	v_mov_b32_e32 v147, s15
	v_or_b32_e32 v146, s14, v168
	v_mov_b32_e32 v145, s15
	v_or_b32_e32 v144, s14, v176
	s_add_i32 s16, s16, s26
	s_add_i32 s17, s17, s55
	s_add_i32 s18, s18, s23
	s_cmpk_lt_i32 s16, 0x800
	s_waitcnt vmcnt(16)
	s_nop 0
	v_add_f32_e32 v60, v56, v58
	v_add_f32_e32 v61, v57, v59
	v_add_f32_e32 v68, v64, v66
	v_add_f32_e32 v69, v65, v67
	v_add_f32_dpp v60, v60, v60 quad_perm:[1,0,3,2] row_mask:0xf bank_mask:0xf
	v_add_f32_dpp v61, v61, v61 quad_perm:[1,0,3,2] row_mask:0xf bank_mask:0xf
	v_add_f32_dpp v68, v68, v68 quad_perm:[1,0,3,2] row_mask:0xf bank_mask:0xf
	v_add_f32_dpp v69, v69, v69 quad_perm:[1,0,3,2] row_mask:0xf bank_mask:0xf
	v_add_f32_dpp v60, v60, v60 quad_perm:[2,3,0,1] row_mask:0xf bank_mask:0xf
	v_add_f32_dpp v61, v61, v61 quad_perm:[2,3,0,1] row_mask:0xf bank_mask:0xf
	v_add_f32_dpp v68, v68, v68 quad_perm:[2,3,0,1] row_mask:0xf bank_mask:0xf
	v_add_f32_dpp v69, v69, v69 quad_perm:[2,3,0,1] row_mask:0xf bank_mask:0xf
	v_add_f32_dpp v60, v60, v60 row_half_mirror row_mask:0xf bank_mask:0xf
	v_add_f32_dpp v61, v61, v61 row_half_mirror row_mask:0xf bank_mask:0xf
	v_add_f32_dpp v68, v68, v68 row_half_mirror row_mask:0xf bank_mask:0xf
	v_add_f32_dpp v69, v69, v69 row_half_mirror row_mask:0xf bank_mask:0xf
	s_nop 1
	v_mov_b32_e32 v128, v61
	v_mul_f32_e32 v129, s44, v60
	s_nop 0
	v_mov_b32_e32 v195, v129
	v_pk_mul_f32 v[58:59], v[128:129], v[194:195]
	s_nop 0
	v_sub_f32_e32 v58, v58, v59
	v_max_f32_e32 v58, 0, v58
	v_add_f32_e32 v58, 0x358637bd, v58
	v_cmp_gt_f32_e32 vcc, s61, v58
	v_mul_f32_e32 v59, 0x4f800000, v58
	s_nop 0
	v_cndmask_b32_e32 v58, v58, v59, vcc
	v_sqrt_f32_e32 v59, v58
	s_nop 0
	v_add_u32_e32 v71, -1, v59
	v_fma_f32 v72, -v71, v59, v58
	v_cmp_ge_f32_e64 s[70:71], 0, v72
	v_add_u32_e32 v72, 1, v59
	s_nop 0
	v_cndmask_b32_e64 v71, v59, v71, s[70:71]
	v_fma_f32 v59, -v72, v59, v58
	v_cmp_lt_f32_e64 s[70:71], 0, v59
	s_nop 1
	v_cndmask_b32_e64 v59, v71, v72, s[70:71]
	v_mul_f32_e32 v71, 0x37800000, v59
	v_cndmask_b32_e32 v59, v59, v71, vcc
	v_cmp_class_f32_e32 vcc, v58, v226
	s_nop 1
	v_cndmask_b32_e32 v58, v59, v58, vcc
	v_div_scale_f32 v59, s[70:71], v58, v58, 1.0
	v_rcp_f32_e32 v71, v59
	s_nop 0
	v_fma_f32 v72, -v59, v71, 1.0
	v_fmac_f32_e32 v71, v72, v71
	v_div_scale_f32 v72, vcc, 1.0, v58, 1.0
	v_mul_f32_e32 v73, v72, v71
	v_fma_f32 v74, -v59, v73, v72
	v_fmac_f32_e32 v73, v74, v71
	v_fma_f32 v59, -v59, v73, v72
	v_div_fmas_f32 v59, v59, v71, v73
	v_div_fixup_f32 v59, v59, v58, 1.0
	v_mov_b32_e32 v61, v59
	v_mov_b32_e32 v128, v69
	v_mul_f32_e32 v129, s44, v68
	s_nop 0
	v_mov_b32_e32 v195, v129
	v_pk_mul_f32 v[58:59], v[128:129], v[194:195]
	s_nop 0
	v_sub_f32_e32 v58, v58, v59
	v_max_f32_e32 v58, 0, v58
	v_add_f32_e32 v58, 0x358637bd, v58
	v_cmp_gt_f32_e32 vcc, s61, v58
	v_mul_f32_e32 v59, 0x4f800000, v58
	s_nop 0
	v_cndmask_b32_e32 v58, v58, v59, vcc
	v_sqrt_f32_e32 v59, v58
	s_nop 0
	v_add_u32_e32 v71, -1, v59
	v_fma_f32 v72, -v71, v59, v58
	v_cmp_ge_f32_e64 s[70:71], 0, v72
	v_add_u32_e32 v72, 1, v59
	s_nop 0
	v_cndmask_b32_e64 v71, v59, v71, s[70:71]
	v_fma_f32 v59, -v72, v59, v58
	v_cmp_lt_f32_e64 s[70:71], 0, v59
	s_nop 1
	v_cndmask_b32_e64 v59, v71, v72, s[70:71]
	v_mul_f32_e32 v71, 0x37800000, v59
	v_cndmask_b32_e32 v59, v59, v71, vcc
	v_cmp_class_f32_e32 vcc, v58, v226
	s_nop 1
	v_cndmask_b32_e32 v58, v59, v58, vcc
	v_div_scale_f32 v59, s[70:71], v58, v58, 1.0
	v_rcp_f32_e32 v71, v59
	s_nop 0
	v_fma_f32 v72, -v59, v71, 1.0
	v_fmac_f32_e32 v71, v72, v71
	v_div_scale_f32 v72, vcc, 1.0, v58, 1.0
	v_mul_f32_e32 v73, v72, v71
	v_fma_f32 v74, -v59, v73, v72
	v_fmac_f32_e32 v73, v74, v71
	v_fma_f32 v59, -v59, v73, v72
	v_div_fmas_f32 v59, v59, v71, v73
	v_div_fixup_f32 v59, v59, v58, 1.0
	v_mov_b32_e32 v69, v59
	v_lshrrev_b32_e32 v77, 1, v76
	v_and_b32_e32 v78, 1, v76
	v_mul_u32_u24_e32 v77, 0x110, v77
	v_lshl_add_u32 v77, v78, 3, v77
	ds_write_b64 v77, v[60:61] offset:256
	ds_write_b64 v77, v[68:69] offset:1344
	v_mul_u32_u24_e32 v77, 0x110, v244
	s_waitcnt lgkmcnt(0)
	s_barrier
	ds_read_b128 v[100:103], v77 offset:256
	s_waitcnt lgkmcnt(0)
	v_mov_b32_e32 v56, v100
	v_mov_b32_e32 v58, v101
	v_mov_b32_e32 v57, v102
	v_mov_b32_e32 v59, v103
	v_mov_b32_e32 v60, s24
	v_mov_b32_e32 v61, s22
	s_waitcnt vmcnt(0)
	ds_write_b128 v107, v[120:123] offset:0
	ds_write_b128 v107, v[48:51] offset:1088
	ds_write_b128 v107, v[40:43] offset:2176
	ds_write_b128 v107, v[32:35] offset:3264
	ds_write_b128 v107, v[24:27] offset:4352
	ds_write_b128 v107, v[16:19] offset:5440
	ds_write_b128 v107, v[8:11] offset:6528
	ds_write_b128 v107, v[0:3] offset:7616
	ds_write_b128 v107, v[124:127] offset:8704
	ds_write_b128 v107, v[52:55] offset:9792
	ds_write_b128 v107, v[44:47] offset:10880
	ds_write_b128 v107, v[36:39] offset:11968
	ds_write_b128 v107, v[28:31] offset:13056
	ds_write_b128 v107, v[20:23] offset:14144
	ds_write_b128 v107, v[12:15] offset:15232
	ds_write_b128 v107, v[4:7] offset:16320
	s_waitcnt lgkmcnt(0)
	ds_read_b128 v[120:123], v104 offset:0
	ds_read_b128 v[124:127], v104 offset:128
	ds_read_b128 v[48:51], v104 offset:16
	ds_read_b128 v[52:55], v104 offset:144
	ds_read_b128 v[40:43], v104 offset:32
	ds_read_b128 v[44:47], v104 offset:160
	ds_read_b128 v[32:35], v104 offset:48
	ds_read_b128 v[36:39], v104 offset:176
	ds_read_b128 v[24:27], v104 offset:64
	ds_read_b128 v[28:31], v104 offset:192
	ds_read_b128 v[16:19], v104 offset:80
	ds_read_b128 v[20:23], v104 offset:208
	ds_read_b128 v[8:11], v104 offset:96
	ds_read_b128 v[12:15], v104 offset:224
	ds_read_b128 v[0:3], v104 offset:112
	ds_read_b128 v[4:7], v104 offset:240
	s_waitcnt lgkmcnt(0)
	ds_read_b128 v[62:65], v60
	ds_read_b128 v[66:69], v60 offset:16
	ds_read_b128 v[92:95], v61
	ds_read_b128 v[96:99], v61 offset:16
	v_lshlrev_b32_e32 v79, 16, v52
	v_lshlrev_b32_e32 v78, 16, v48
	v_and_b32_e32 v81, 0xffff0000, v52
	v_and_b32_e32 v80, 0xffff0000, v48
	v_pk_fma_f32 v[78:79], v[56:57], s[44:45], v[78:79] op_sel_hi:[1,0,1] neg_lo:[1,0,0] neg_hi:[1,0,0]
	v_pk_fma_f32 v[80:81], v[56:57], s[44:45], v[80:81] op_sel_hi:[1,0,1] neg_lo:[1,0,0] neg_hi:[1,0,0]
	v_lshlrev_b32_e32 v71, 16, v124
	v_lshlrev_b32_e32 v70, 16, v120
	v_and_b32_e32 v73, 0xffff0000, v124
	v_and_b32_e32 v72, 0xffff0000, v120
	v_pk_fma_f32 v[70:71], v[56:57], s[44:45], v[70:71] op_sel_hi:[1,0,1] neg_lo:[1,0,0] neg_hi:[1,0,0]
	v_pk_fma_f32 v[72:73], v[56:57], s[44:45], v[72:73] op_sel_hi:[1,0,1] neg_lo:[1,0,0] neg_hi:[1,0,0]
	v_pk_mul_f32 v[70:71], v[70:71], v[58:59]
	v_pk_mul_f32 v[72:73], v[72:73], v[58:59]
	s_waitcnt lgkmcnt(1)
	v_pk_fma_f32 v[70:71], v[62:63], v[70:71], v[92:93] op_sel_hi:[0,1,0]
	v_pk_fma_f32 v[62:63], v[62:63], v[72:73], v[92:93] op_sel:[1,0,1]
	v_cvt_pk_bf16_f32 v70, v70, v71
	v_cvt_pk_bf16_f32 v62, v62, v63
	ds_write2_b32 v161, v70, v62 offset1:68
	v_lshlrev_b32_e32 v63, 16, v125
	v_lshlrev_b32_e32 v62, 16, v121
	v_pk_fma_f32 v[62:63], v[56:57], s[44:45], v[62:63] op_sel_hi:[1,0,1] neg_lo:[1,0,0] neg_hi:[1,0,0]
	v_and_b32_e32 v71, 0xffff0000, v125
	v_and_b32_e32 v70, 0xffff0000, v121
	v_pk_mul_f32 v[62:63], v[62:63], v[58:59]
	v_pk_fma_f32 v[70:71], v[56:57], s[44:45], v[70:71] op_sel_hi:[1,0,1] neg_lo:[1,0,0] neg_hi:[1,0,0]
	v_pk_fma_f32 v[62:63], v[64:65], v[62:63], v[94:95] op_sel_hi:[0,1,0]
	v_pk_mul_f32 v[70:71], v[70:71], v[58:59]
	v_mov_b32_e32 v64, v65
	v_mov_b32_e32 v72, v95
	v_pk_fma_f32 v[64:65], v[64:65], v[70:71], v[72:73] op_sel_hi:[0,1,0]
	v_cvt_pk_bf16_f32 v62, v62, v63
	v_cvt_pk_bf16_f32 v63, v64, v65
	ds_write2_b32 v161, v62, v63 offset0:136 offset1:204
	v_lshlrev_b32_e32 v63, 16, v126
	v_lshlrev_b32_e32 v62, 16, v122
	v_and_b32_e32 v65, 0xffff0000, v126
	v_and_b32_e32 v64, 0xffff0000, v122
	v_pk_fma_f32 v[62:63], v[56:57], s[44:45], v[62:63] op_sel_hi:[1,0,1] neg_lo:[1,0,0] neg_hi:[1,0,0]
	v_pk_fma_f32 v[64:65], v[56:57], s[44:45], v[64:65] op_sel_hi:[1,0,1] neg_lo:[1,0,0] neg_hi:[1,0,0]
	v_pk_mul_f32 v[62:63], v[62:63], v[58:59]
	v_pk_mul_f32 v[64:65], v[64:65], v[58:59]
	s_waitcnt lgkmcnt(2)
	v_pk_fma_f32 v[62:63], v[66:67], v[62:63], v[96:97] op_sel_hi:[0,1,0]
	v_pk_fma_f32 v[64:65], v[66:67], v[64:65], v[96:97] op_sel:[1,0,1]
	v_cvt_pk_bf16_f32 v62, v62, v63
	v_cvt_pk_bf16_f32 v63, v64, v65
	v_add_u32_e32 v67, 0x800, v161
	ds_write2_b32 v67, v62, v63 offset0:32 offset1:100
	v_lshlrev_b32_e32 v63, 16, v127
	v_lshlrev_b32_e32 v62, 16, v123
	v_pk_fma_f32 v[62:63], v[56:57], s[44:45], v[62:63] op_sel_hi:[1,0,1] neg_lo:[1,0,0] neg_hi:[1,0,0]
	v_and_b32_e32 v65, 0xffff0000, v127
	v_and_b32_e32 v64, 0xffff0000, v123
	v_pk_mul_f32 v[62:63], v[62:63], v[58:59]
	v_pk_fma_f32 v[64:65], v[56:57], s[44:45], v[64:65] op_sel_hi:[1,0,1] neg_lo:[1,0,0] neg_hi:[1,0,0]
	v_pk_fma_f32 v[62:63], v[68:69], v[62:63], v[98:99] op_sel_hi:[0,1,0]
	v_pk_mul_f32 v[64:65], v[64:65], v[58:59]
	v_mov_b32_e32 v66, v69
	v_mov_b32_e32 v68, v99
	v_pk_fma_f32 v[64:65], v[66:67], v[64:65], v[68:69] op_sel_hi:[0,1,0]
	v_cvt_pk_bf16_f32 v62, v62, v63
	v_cvt_pk_bf16_f32 v63, v64, v65
	ds_write2_b32 v67, v62, v63 offset0:168 offset1:236
	ds_read_b128 v[62:65], v60 offset:32
	ds_read_b128 v[66:69], v60 offset:48
	ds_read_b128 v[70:73], v61 offset:32
	ds_read_b128 v[74:77], v61 offset:48
	v_pk_mul_f32 v[78:79], v[78:79], v[58:59]
	v_pk_mul_f32 v[80:81], v[80:81], v[58:59]
	s_waitcnt lgkmcnt(1)
	v_pk_fma_f32 v[78:79], v[62:63], v[78:79], v[70:71] op_sel_hi:[0,1,0]
	v_pk_fma_f32 v[62:63], v[62:63], v[80:81], v[70:71] op_sel:[1,0,1]
	v_cvt_pk_bf16_f32 v48, v78, v79
	v_cvt_pk_bf16_f32 v52, v62, v63
	v_add_u32_e32 v62, 0x1000, v161
	ds_write2_b32 v62, v48, v52 offset0:64 offset1:132
	v_lshlrev_b32_e32 v63, 16, v53
	v_lshlrev_b32_e32 v62, 16, v49
	v_pk_fma_f32 v[62:63], v[56:57], s[44:45], v[62:63] op_sel_hi:[1,0,1] neg_lo:[1,0,0] neg_hi:[1,0,0]
	v_and_b32_e32 v53, 0xffff0000, v53
	v_and_b32_e32 v52, 0xffff0000, v49
	v_pk_mul_f32 v[62:63], v[62:63], v[58:59]
	v_pk_fma_f32 v[48:49], v[56:57], s[44:45], v[52:53] op_sel_hi:[1,0,1] neg_lo:[1,0,0] neg_hi:[1,0,0]
	v_pk_fma_f32 v[62:63], v[64:65], v[62:63], v[72:73] op_sel_hi:[0,1,0]
	v_pk_mul_f32 v[48:49], v[48:49], v[58:59]
	v_mov_b32_e32 v52, v65
	v_mov_b32_e32 v64, v73
	v_pk_fma_f32 v[48:49], v[52:53], v[48:49], v[64:65] op_sel_hi:[0,1,0]
	v_cvt_pk_bf16_f32 v52, v62, v63
	v_cvt_pk_bf16_f32 v48, v48, v49
	v_add_u32_e32 v49, 0x1200, v161
	ds_write2_b32 v49, v52, v48 offset0:72 offset1:140
	v_lshlrev_b32_e32 v49, 16, v54
	v_lshlrev_b32_e32 v48, 16, v50
	v_and_b32_e32 v53, 0xffff0000, v54
	v_and_b32_e32 v52, 0xffff0000, v50
	v_pk_fma_f32 v[48:49], v[56:57], s[44:45], v[48:49] op_sel_hi:[1,0,1] neg_lo:[1,0,0] neg_hi:[1,0,0]
	v_pk_fma_f32 v[52:53], v[56:57], s[44:45], v[52:53] op_sel_hi:[1,0,1] neg_lo:[1,0,0] neg_hi:[1,0,0]
	v_pk_mul_f32 v[48:49], v[48:49], v[58:59]
	v_pk_mul_f32 v[52:53], v[52:53], v[58:59]
	s_waitcnt lgkmcnt(2)
	v_pk_fma_f32 v[48:49], v[66:67], v[48:49], v[74:75] op_sel_hi:[0,1,0]
	v_pk_fma_f32 v[52:53], v[66:67], v[52:53], v[74:75] op_sel:[1,0,1]
	v_cvt_pk_bf16_f32 v48, v48, v49
	v_cvt_pk_bf16_f32 v49, v52, v53
	v_add_u32_e32 v50, 0x1800, v161
	ds_write2_b32 v50, v48, v49 offset0:96 offset1:164
	v_lshlrev_b32_e32 v49, 16, v55
	v_lshlrev_b32_e32 v48, 16, v51
	v_and_b32_e32 v53, 0xffff0000, v55
	v_and_b32_e32 v52, 0xffff0000, v51
	v_pk_fma_f32 v[48:49], v[56:57], s[44:45], v[48:49] op_sel_hi:[1,0,1] neg_lo:[1,0,0] neg_hi:[1,0,0]
	v_pk_fma_f32 v[50:51], v[56:57], s[44:45], v[52:53] op_sel_hi:[1,0,1] neg_lo:[1,0,0] neg_hi:[1,0,0]
	v_pk_mul_f32 v[48:49], v[48:49], v[58:59]
	v_pk_mul_f32 v[50:51], v[50:51], v[58:59]
	v_mov_b32_e32 v52, v69
	v_mov_b32_e32 v54, v77
	v_pk_fma_f32 v[48:49], v[68:69], v[48:49], v[76:77] op_sel_hi:[0,1,0]
	v_pk_fma_f32 v[50:51], v[52:53], v[50:51], v[54:55] op_sel_hi:[0,1,0]
	v_cvt_pk_bf16_f32 v48, v48, v49
	v_cvt_pk_bf16_f32 v49, v50, v51
	v_add_u32_e32 v50, 0x1a00, v161
	ds_write2_b32 v50, v48, v49 offset0:104 offset1:172
	ds_read_b128 v[48:51], v60 offset:64
	ds_read_b128 v[52:55], v60 offset:80
	ds_read_b128 v[62:65], v61 offset:64
	ds_read_b128 v[66:69], v61 offset:80
	v_lshlrev_b32_e32 v71, 16, v44
	v_lshlrev_b32_e32 v70, 16, v40
	v_and_b32_e32 v73, 0xffff0000, v44
	v_and_b32_e32 v72, 0xffff0000, v40
	v_pk_fma_f32 v[70:71], v[56:57], s[44:45], v[70:71] op_sel_hi:[1,0,1] neg_lo:[1,0,0] neg_hi:[1,0,0]
	v_pk_fma_f32 v[72:73], v[56:57], s[44:45], v[72:73] op_sel_hi:[1,0,1] neg_lo:[1,0,0] neg_hi:[1,0,0]
	v_pk_mul_f32 v[70:71], v[70:71], v[58:59]
	v_pk_mul_f32 v[72:73], v[72:73], v[58:59]
	s_waitcnt lgkmcnt(1)
	v_pk_fma_f32 v[70:71], v[70:71], v[48:49], v[62:63] op_sel_hi:[1,0,0]
	v_pk_fma_f32 v[48:49], v[72:73], v[48:49], v[62:63] op_sel:[0,1,1]
	v_cvt_pk_bf16_f32 v40, v70, v71
	v_cvt_pk_bf16_f32 v44, v48, v49
	v_add_u32_e32 v62, 0x400, v161
	v_lshlrev_b32_e32 v49, 16, v45
	v_lshlrev_b32_e32 v48, 16, v41
	ds_write2_b32 v62, v40, v44 offset0:16 offset1:84
	v_pk_fma_f32 v[48:49], v[56:57], s[44:45], v[48:49] op_sel_hi:[1,0,1] neg_lo:[1,0,0] neg_hi:[1,0,0]
	v_and_b32_e32 v45, 0xffff0000, v45
	v_and_b32_e32 v44, 0xffff0000, v41
	v_pk_mul_f32 v[48:49], v[48:49], v[58:59]
	v_pk_fma_f32 v[40:41], v[56:57], s[44:45], v[44:45] op_sel_hi:[1,0,1] neg_lo:[1,0,0] neg_hi:[1,0,0]
	v_pk_fma_f32 v[48:49], v[48:49], v[50:51], v[64:65] op_sel_hi:[1,0,0]
	v_pk_mul_f32 v[40:41], v[40:41], v[58:59]
	v_mov_b32_e32 v44, v51
	v_mov_b32_e32 v50, v65
	v_pk_fma_f32 v[40:41], v[40:41], v[44:45], v[50:51] op_sel_hi:[1,0,0]
	v_cvt_pk_bf16_f32 v44, v48, v49
	v_cvt_pk_bf16_f32 v40, v40, v41
	ds_write2_b32 v62, v44, v40 offset0:152 offset1:220
	v_lshlrev_b32_e32 v41, 16, v46
	v_lshlrev_b32_e32 v40, 16, v42
	v_and_b32_e32 v45, 0xffff0000, v46
	v_and_b32_e32 v44, 0xffff0000, v42
	v_pk_fma_f32 v[40:41], v[56:57], s[44:45], v[40:41] op_sel_hi:[1,0,1] neg_lo:[1,0,0] neg_hi:[1,0,0]
	v_pk_fma_f32 v[44:45], v[56:57], s[44:45], v[44:45] op_sel_hi:[1,0,1] neg_lo:[1,0,0] neg_hi:[1,0,0]
	v_pk_mul_f32 v[40:41], v[40:41], v[58:59]
	v_pk_mul_f32 v[44:45], v[44:45], v[58:59]
	s_waitcnt lgkmcnt(2)
	v_pk_fma_f32 v[40:41], v[40:41], v[52:53], v[66:67] op_sel_hi:[1,0,0]
	v_pk_fma_f32 v[44:45], v[44:45], v[52:53], v[66:67] op_sel:[0,1,1]
	v_cvt_pk_bf16_f32 v40, v40, v41
	v_cvt_pk_bf16_f32 v41, v44, v45
	v_add_u32_e32 v48, 0xc00, v161
	ds_write2_b32 v48, v40, v41 offset0:48 offset1:116
	v_lshlrev_b32_e32 v41, 16, v47
	v_lshlrev_b32_e32 v40, 16, v43
	v_and_b32_e32 v45, 0xffff0000, v47
	v_and_b32_e32 v44, 0xffff0000, v43
	v_pk_fma_f32 v[40:41], v[56:57], s[44:45], v[40:41] op_sel_hi:[1,0,1] neg_lo:[1,0,0] neg_hi:[1,0,0]
	v_pk_fma_f32 v[42:43], v[56:57], s[44:45], v[44:45] op_sel_hi:[1,0,1] neg_lo:[1,0,0] neg_hi:[1,0,0]
	v_pk_mul_f32 v[40:41], v[40:41], v[58:59]
	v_pk_mul_f32 v[42:43], v[42:43], v[58:59]
	v_mov_b32_e32 v44, v55
	v_mov_b32_e32 v46, v69
	v_pk_fma_f32 v[40:41], v[40:41], v[54:55], v[68:69] op_sel_hi:[1,0,0]
	v_pk_fma_f32 v[42:43], v[42:43], v[44:45], v[46:47] op_sel_hi:[1,0,0]
	v_cvt_pk_bf16_f32 v40, v40, v41
	v_cvt_pk_bf16_f32 v41, v42, v43
	ds_write2_b32 v48, v40, v41 offset0:184 offset1:252
	ds_read_b128 v[40:43], v60 offset:96
	ds_read_b128 v[44:47], v60 offset:112
	ds_read_b128 v[48:51], v61 offset:96
	ds_read_b128 v[52:55], v61 offset:112
	v_lshlrev_b32_e32 v63, 16, v36
	v_lshlrev_b32_e32 v62, 16, v32
	v_and_b32_e32 v65, 0xffff0000, v36
	v_and_b32_e32 v64, 0xffff0000, v32
	v_pk_fma_f32 v[62:63], v[56:57], s[44:45], v[62:63] op_sel_hi:[1,0,1] neg_lo:[1,0,0] neg_hi:[1,0,0]
	v_pk_fma_f32 v[64:65], v[56:57], s[44:45], v[64:65] op_sel_hi:[1,0,1] neg_lo:[1,0,0] neg_hi:[1,0,0]
	v_pk_mul_f32 v[62:63], v[62:63], v[58:59]
	v_pk_mul_f32 v[64:65], v[64:65], v[58:59]
	s_waitcnt lgkmcnt(1)
	v_pk_fma_f32 v[62:63], v[62:63], v[40:41], v[48:49] op_sel_hi:[1,0,0]
	v_pk_fma_f32 v[40:41], v[64:65], v[40:41], v[48:49] op_sel:[0,1,1]
	v_cvt_pk_bf16_f32 v32, v62, v63
	v_cvt_pk_bf16_f32 v36, v40, v41
	v_add_u32_e32 v40, 0x1400, v161
	ds_write2_b32 v40, v32, v36 offset0:80 offset1:148
	v_lshlrev_b32_e32 v41, 16, v37
	v_lshlrev_b32_e32 v40, 16, v33
	v_pk_fma_f32 v[40:41], v[56:57], s[44:45], v[40:41] op_sel_hi:[1,0,1] neg_lo:[1,0,0] neg_hi:[1,0,0]
	v_and_b32_e32 v37, 0xffff0000, v37
	v_and_b32_e32 v36, 0xffff0000, v33
	v_pk_mul_f32 v[40:41], v[40:41], v[58:59]
	v_pk_fma_f32 v[32:33], v[56:57], s[44:45], v[36:37] op_sel_hi:[1,0,1] neg_lo:[1,0,0] neg_hi:[1,0,0]
	v_pk_fma_f32 v[40:41], v[40:41], v[42:43], v[50:51] op_sel_hi:[1,0,0]
	v_pk_mul_f32 v[32:33], v[32:33], v[58:59]
	v_mov_b32_e32 v36, v43
	v_mov_b32_e32 v42, v51
	v_pk_fma_f32 v[32:33], v[32:33], v[36:37], v[42:43] op_sel_hi:[1,0,0]
	v_cvt_pk_bf16_f32 v36, v40, v41
	v_cvt_pk_bf16_f32 v32, v32, v33
	v_add_u32_e32 v33, 0x1600, v161
	ds_write2_b32 v33, v36, v32 offset0:88 offset1:156
	v_lshlrev_b32_e32 v33, 16, v38
	v_lshlrev_b32_e32 v32, 16, v34
	v_and_b32_e32 v37, 0xffff0000, v38
	v_and_b32_e32 v36, 0xffff0000, v34
	v_pk_fma_f32 v[32:33], v[56:57], s[44:45], v[32:33] op_sel_hi:[1,0,1] neg_lo:[1,0,0] neg_hi:[1,0,0]
	v_pk_fma_f32 v[36:37], v[56:57], s[44:45], v[36:37] op_sel_hi:[1,0,1] neg_lo:[1,0,0] neg_hi:[1,0,0]
	v_pk_mul_f32 v[32:33], v[32:33], v[58:59]
	v_pk_mul_f32 v[36:37], v[36:37], v[58:59]
	s_waitcnt lgkmcnt(2)
	v_pk_fma_f32 v[32:33], v[32:33], v[44:45], v[52:53] op_sel_hi:[1,0,0]
	v_pk_fma_f32 v[36:37], v[36:37], v[44:45], v[52:53] op_sel:[0,1,1]
	v_cvt_pk_bf16_f32 v32, v32, v33
	v_cvt_pk_bf16_f32 v33, v36, v37
	v_add_u32_e32 v34, 0x1c00, v161
	ds_write2_b32 v34, v32, v33 offset0:112 offset1:180
	v_lshlrev_b32_e32 v33, 16, v39
	v_lshlrev_b32_e32 v32, 16, v35
	v_and_b32_e32 v37, 0xffff0000, v39
	v_and_b32_e32 v36, 0xffff0000, v35
	v_pk_fma_f32 v[32:33], v[56:57], s[44:45], v[32:33] op_sel_hi:[1,0,1] neg_lo:[1,0,0] neg_hi:[1,0,0]
	v_pk_fma_f32 v[34:35], v[56:57], s[44:45], v[36:37] op_sel_hi:[1,0,1] neg_lo:[1,0,0] neg_hi:[1,0,0]
	v_pk_mul_f32 v[32:33], v[32:33], v[58:59]
	v_pk_mul_f32 v[34:35], v[34:35], v[58:59]
	v_mov_b32_e32 v36, v47
	v_mov_b32_e32 v38, v55
	v_pk_fma_f32 v[32:33], v[32:33], v[46:47], v[54:55] op_sel_hi:[1,0,0]
	v_pk_fma_f32 v[34:35], v[34:35], v[36:37], v[38:39] op_sel_hi:[1,0,0]
	v_cvt_pk_bf16_f32 v32, v32, v33
	v_cvt_pk_bf16_f32 v33, v34, v35
	v_add_u32_e32 v34, 0x1e00, v161
	ds_write2_b32 v34, v32, v33 offset0:120 offset1:188
	ds_read_b128 v[32:35], v60 offset:128
	ds_read_b128 v[36:39], v60 offset:144
	ds_read_b128 v[40:43], v61 offset:128
	ds_read_b128 v[44:47], v61 offset:144
	v_lshlrev_b32_e32 v49, 16, v28
	v_lshlrev_b32_e32 v48, 16, v24
	v_and_b32_e32 v51, 0xffff0000, v28
	v_and_b32_e32 v50, 0xffff0000, v24
	v_pk_fma_f32 v[48:49], v[56:57], s[44:45], v[48:49] op_sel_hi:[1,0,1] neg_lo:[1,0,0] neg_hi:[1,0,0]
	v_pk_fma_f32 v[50:51], v[56:57], s[44:45], v[50:51] op_sel_hi:[1,0,1] neg_lo:[1,0,0] neg_hi:[1,0,0]
	v_pk_mul_f32 v[48:49], v[48:49], v[58:59]
	v_pk_mul_f32 v[50:51], v[50:51], v[58:59]
	s_waitcnt lgkmcnt(1)
	v_pk_fma_f32 v[48:49], v[48:49], v[32:33], v[40:41] op_sel_hi:[1,0,0]
	v_pk_fma_f32 v[32:33], v[50:51], v[32:33], v[40:41] op_sel:[0,1,1]
	v_cvt_pk_bf16_f32 v24, v48, v49
	v_cvt_pk_bf16_f32 v28, v32, v33
	v_add_u32_e32 v32, 0x2000, v161
	ds_write2_b32 v32, v24, v28 offset0:128 offset1:196
	v_lshlrev_b32_e32 v33, 16, v29
	v_lshlrev_b32_e32 v32, 16, v25
	v_pk_fma_f32 v[32:33], v[56:57], s[44:45], v[32:33] op_sel_hi:[1,0,1] neg_lo:[1,0,0] neg_hi:[1,0,0]
	v_and_b32_e32 v29, 0xffff0000, v29
	v_and_b32_e32 v28, 0xffff0000, v25
	v_pk_mul_f32 v[32:33], v[32:33], v[58:59]
	v_pk_fma_f32 v[24:25], v[56:57], s[44:45], v[28:29] op_sel_hi:[1,0,1] neg_lo:[1,0,0] neg_hi:[1,0,0]
	v_pk_fma_f32 v[32:33], v[32:33], v[34:35], v[42:43] op_sel_hi:[1,0,0]
	v_pk_mul_f32 v[24:25], v[24:25], v[58:59]
	v_mov_b32_e32 v28, v35
	v_mov_b32_e32 v34, v43
	v_pk_fma_f32 v[24:25], v[24:25], v[28:29], v[34:35] op_sel_hi:[1,0,0]
	v_cvt_pk_bf16_f32 v28, v32, v33
	v_cvt_pk_bf16_f32 v24, v24, v25
	v_add_u32_e32 v48, 0x2400, v161
	ds_write2_b32 v48, v28, v24 offset0:8 offset1:76
	v_lshlrev_b32_e32 v25, 16, v30
	v_lshlrev_b32_e32 v24, 16, v26
	v_and_b32_e32 v29, 0xffff0000, v30
	v_and_b32_e32 v28, 0xffff0000, v26
	v_pk_fma_f32 v[24:25], v[56:57], s[44:45], v[24:25] op_sel_hi:[1,0,1] neg_lo:[1,0,0] neg_hi:[1,0,0]
	v_pk_fma_f32 v[28:29], v[56:57], s[44:45], v[28:29] op_sel_hi:[1,0,1] neg_lo:[1,0,0] neg_hi:[1,0,0]
	v_pk_mul_f32 v[24:25], v[24:25], v[58:59]
	v_pk_mul_f32 v[28:29], v[28:29], v[58:59]
	s_waitcnt lgkmcnt(2)
	v_pk_fma_f32 v[24:25], v[24:25], v[36:37], v[44:45] op_sel_hi:[1,0,0]
	v_pk_fma_f32 v[28:29], v[28:29], v[36:37], v[44:45] op_sel:[0,1,1]
	v_cvt_pk_bf16_f32 v24, v24, v25
	v_cvt_pk_bf16_f32 v25, v28, v29
	v_add_u32_e32 v44, 0x2800, v161
	ds_write2_b32 v44, v24, v25 offset0:160 offset1:228
	v_lshlrev_b32_e32 v25, 16, v31
	v_lshlrev_b32_e32 v24, 16, v27
	v_and_b32_e32 v29, 0xffff0000, v31
	v_and_b32_e32 v28, 0xffff0000, v27
	v_pk_fma_f32 v[24:25], v[56:57], s[44:45], v[24:25] op_sel_hi:[1,0,1] neg_lo:[1,0,0] neg_hi:[1,0,0]
	v_pk_fma_f32 v[26:27], v[56:57], s[44:45], v[28:29] op_sel_hi:[1,0,1] neg_lo:[1,0,0] neg_hi:[1,0,0]
	v_pk_mul_f32 v[24:25], v[24:25], v[58:59]
	v_pk_mul_f32 v[26:27], v[26:27], v[58:59]
	v_mov_b32_e32 v28, v39
	v_mov_b32_e32 v30, v47
	v_pk_fma_f32 v[24:25], v[24:25], v[38:39], v[46:47] op_sel_hi:[1,0,0]
	v_pk_fma_f32 v[26:27], v[26:27], v[28:29], v[30:31] op_sel_hi:[1,0,0]
	v_cvt_pk_bf16_f32 v24, v24, v25
	v_cvt_pk_bf16_f32 v25, v26, v27
	v_add_u32_e32 v45, 0x2c00, v161
	ds_write2_b32 v45, v24, v25 offset0:40 offset1:108
	ds_read_b128 v[24:27], v60 offset:160
	ds_read_b128 v[28:31], v60 offset:176
	ds_read_b128 v[32:35], v61 offset:160
	ds_read_b128 v[36:39], v61 offset:176
	v_lshlrev_b32_e32 v41, 16, v20
	v_lshlrev_b32_e32 v40, 16, v16
	v_and_b32_e32 v43, 0xffff0000, v20
	v_and_b32_e32 v42, 0xffff0000, v16
	v_pk_fma_f32 v[40:41], v[56:57], s[44:45], v[40:41] op_sel_hi:[1,0,1] neg_lo:[1,0,0] neg_hi:[1,0,0]
	v_pk_fma_f32 v[42:43], v[56:57], s[44:45], v[42:43] op_sel_hi:[1,0,1] neg_lo:[1,0,0] neg_hi:[1,0,0]
	v_pk_mul_f32 v[40:41], v[40:41], v[58:59]
	v_pk_mul_f32 v[42:43], v[42:43], v[58:59]
	s_waitcnt lgkmcnt(1)
	v_pk_fma_f32 v[40:41], v[40:41], v[24:25], v[32:33] op_sel_hi:[1,0,0]
	v_pk_fma_f32 v[24:25], v[42:43], v[24:25], v[32:33] op_sel:[0,1,1]
	v_cvt_pk_bf16_f32 v16, v40, v41
	v_cvt_pk_bf16_f32 v20, v24, v25
	v_add_u32_e32 v24, 0x3200, v161
	ds_write2_b32 v24, v16, v20 offset0:64 offset1:132
	v_lshlrev_b32_e32 v25, 16, v21
	v_lshlrev_b32_e32 v24, 16, v17
	v_pk_fma_f32 v[24:25], v[56:57], s[44:45], v[24:25] op_sel_hi:[1,0,1] neg_lo:[1,0,0] neg_hi:[1,0,0]
	v_and_b32_e32 v21, 0xffff0000, v21
	v_and_b32_e32 v20, 0xffff0000, v17
	v_pk_mul_f32 v[24:25], v[24:25], v[58:59]
	v_pk_fma_f32 v[16:17], v[56:57], s[44:45], v[20:21] op_sel_hi:[1,0,1] neg_lo:[1,0,0] neg_hi:[1,0,0]
	v_pk_fma_f32 v[24:25], v[24:25], v[26:27], v[34:35] op_sel_hi:[1,0,0]
	v_pk_mul_f32 v[16:17], v[16:17], v[58:59]
	v_mov_b32_e32 v20, v27
	v_mov_b32_e32 v26, v35
	v_pk_fma_f32 v[16:17], v[16:17], v[20:21], v[26:27] op_sel_hi:[1,0,0]
	v_cvt_pk_bf16_f32 v20, v24, v25
	v_cvt_pk_bf16_f32 v16, v16, v17
	v_add_u32_e32 v17, 0x3400, v161
	ds_write2_b32 v17, v20, v16 offset0:72 offset1:140
	v_lshlrev_b32_e32 v17, 16, v22
	v_lshlrev_b32_e32 v16, 16, v18
	v_and_b32_e32 v21, 0xffff0000, v22
	v_and_b32_e32 v20, 0xffff0000, v18
	v_pk_fma_f32 v[16:17], v[56:57], s[44:45], v[16:17] op_sel_hi:[1,0,1] neg_lo:[1,0,0] neg_hi:[1,0,0]
	v_pk_fma_f32 v[20:21], v[56:57], s[44:45], v[20:21] op_sel_hi:[1,0,1] neg_lo:[1,0,0] neg_hi:[1,0,0]
	v_pk_mul_f32 v[16:17], v[16:17], v[58:59]
	v_pk_mul_f32 v[20:21], v[20:21], v[58:59]
	s_waitcnt lgkmcnt(2)
	v_pk_fma_f32 v[16:17], v[16:17], v[28:29], v[36:37] op_sel_hi:[1,0,0]
	v_pk_fma_f32 v[20:21], v[20:21], v[28:29], v[36:37] op_sel:[0,1,1]
	v_cvt_pk_bf16_f32 v16, v16, v17
	v_cvt_pk_bf16_f32 v17, v20, v21
	v_add_u32_e32 v18, 0x3a00, v161
	ds_write2_b32 v18, v16, v17 offset0:96 offset1:164
	v_lshlrev_b32_e32 v17, 16, v23
	v_lshlrev_b32_e32 v16, 16, v19
	v_and_b32_e32 v21, 0xffff0000, v23
	v_and_b32_e32 v20, 0xffff0000, v19
	v_pk_fma_f32 v[16:17], v[56:57], s[44:45], v[16:17] op_sel_hi:[1,0,1] neg_lo:[1,0,0] neg_hi:[1,0,0]
	v_pk_fma_f32 v[18:19], v[56:57], s[44:45], v[20:21] op_sel_hi:[1,0,1] neg_lo:[1,0,0] neg_hi:[1,0,0]
	v_pk_mul_f32 v[16:17], v[16:17], v[58:59]
	v_pk_mul_f32 v[18:19], v[18:19], v[58:59]
	v_mov_b32_e32 v20, v31
	v_mov_b32_e32 v22, v39
	v_pk_fma_f32 v[16:17], v[16:17], v[30:31], v[38:39] op_sel_hi:[1,0,0]
	v_pk_fma_f32 v[18:19], v[18:19], v[20:21], v[22:23] op_sel_hi:[1,0,0]
	v_cvt_pk_bf16_f32 v16, v16, v17
	v_cvt_pk_bf16_f32 v17, v18, v19
	v_add_u32_e32 v18, 0x3c00, v161
	ds_write2_b32 v18, v16, v17 offset0:104 offset1:172
	ds_read_b128 v[16:19], v60 offset:192
	ds_read_b128 v[20:23], v60 offset:208
	ds_read_b128 v[24:27], v61 offset:192
	ds_read_b128 v[28:31], v61 offset:208
	v_lshlrev_b32_e32 v33, 16, v12
	v_lshlrev_b32_e32 v32, 16, v8
	v_and_b32_e32 v35, 0xffff0000, v12
	v_and_b32_e32 v34, 0xffff0000, v8
	v_pk_fma_f32 v[32:33], v[56:57], s[44:45], v[32:33] op_sel_hi:[1,0,1] neg_lo:[1,0,0] neg_hi:[1,0,0]
	v_pk_fma_f32 v[34:35], v[56:57], s[44:45], v[34:35] op_sel_hi:[1,0,1] neg_lo:[1,0,0] neg_hi:[1,0,0]
	v_pk_mul_f32 v[32:33], v[32:33], v[58:59]
	v_pk_mul_f32 v[34:35], v[34:35], v[58:59]
	s_waitcnt lgkmcnt(1)
	v_pk_fma_f32 v[32:33], v[32:33], v[16:17], v[24:25] op_sel_hi:[1,0,0]
	v_pk_fma_f32 v[16:17], v[34:35], v[16:17], v[24:25] op_sel:[0,1,1]
	v_cvt_pk_bf16_f32 v8, v32, v33
	v_cvt_pk_bf16_f32 v12, v16, v17
	v_lshlrev_b32_e32 v17, 16, v13
	v_lshlrev_b32_e32 v16, 16, v9
	ds_write2_b32 v48, v8, v12 offset0:144 offset1:212
	v_pk_fma_f32 v[16:17], v[56:57], s[44:45], v[16:17] op_sel_hi:[1,0,1] neg_lo:[1,0,0] neg_hi:[1,0,0]
	v_and_b32_e32 v13, 0xffff0000, v13
	v_and_b32_e32 v12, 0xffff0000, v9
	v_pk_mul_f32 v[16:17], v[16:17], v[58:59]
	v_pk_fma_f32 v[8:9], v[56:57], s[44:45], v[12:13] op_sel_hi:[1,0,1] neg_lo:[1,0,0] neg_hi:[1,0,0]
	v_pk_fma_f32 v[16:17], v[16:17], v[18:19], v[26:27] op_sel_hi:[1,0,0]
	v_pk_mul_f32 v[8:9], v[8:9], v[58:59]
	v_mov_b32_e32 v12, v19
	v_mov_b32_e32 v18, v27
	v_pk_fma_f32 v[8:9], v[8:9], v[12:13], v[18:19] op_sel_hi:[1,0,0]
	v_cvt_pk_bf16_f32 v12, v16, v17
	v_cvt_pk_bf16_f32 v8, v8, v9
	ds_write2_b32 v44, v12, v8 offset0:24 offset1:92
	v_lshlrev_b32_e32 v9, 16, v14
	v_lshlrev_b32_e32 v8, 16, v10
	v_and_b32_e32 v13, 0xffff0000, v14
	v_and_b32_e32 v12, 0xffff0000, v10
	v_pk_fma_f32 v[8:9], v[56:57], s[44:45], v[8:9] op_sel_hi:[1,0,1] neg_lo:[1,0,0] neg_hi:[1,0,0]
	v_pk_fma_f32 v[12:13], v[56:57], s[44:45], v[12:13] op_sel_hi:[1,0,1] neg_lo:[1,0,0] neg_hi:[1,0,0]
	v_pk_mul_f32 v[8:9], v[8:9], v[58:59]
	v_pk_mul_f32 v[12:13], v[12:13], v[58:59]
	s_waitcnt lgkmcnt(2)
	v_pk_fma_f32 v[8:9], v[8:9], v[20:21], v[28:29] op_sel_hi:[1,0,0]
	v_pk_fma_f32 v[12:13], v[12:13], v[20:21], v[28:29] op_sel:[0,1,1]
	v_cvt_pk_bf16_f32 v8, v8, v9
	v_cvt_pk_bf16_f32 v9, v12, v13
	ds_write2_b32 v45, v8, v9 offset0:176 offset1:244
	v_lshlrev_b32_e32 v9, 16, v15
	v_lshlrev_b32_e32 v8, 16, v11
	v_and_b32_e32 v13, 0xffff0000, v15
	v_and_b32_e32 v12, 0xffff0000, v11
	v_pk_fma_f32 v[8:9], v[56:57], s[44:45], v[8:9] op_sel_hi:[1,0,1] neg_lo:[1,0,0] neg_hi:[1,0,0]
	v_pk_fma_f32 v[10:11], v[56:57], s[44:45], v[12:13] op_sel_hi:[1,0,1] neg_lo:[1,0,0] neg_hi:[1,0,0]
	v_pk_mul_f32 v[8:9], v[8:9], v[58:59]
	v_pk_mul_f32 v[10:11], v[10:11], v[58:59]
	v_mov_b32_e32 v12, v23
	v_mov_b32_e32 v14, v31
	v_pk_fma_f32 v[8:9], v[8:9], v[22:23], v[30:31] op_sel_hi:[1,0,0]
	v_pk_fma_f32 v[10:11], v[10:11], v[12:13], v[14:15] op_sel_hi:[1,0,0]
	v_cvt_pk_bf16_f32 v8, v8, v9
	v_cvt_pk_bf16_f32 v9, v10, v11
	v_add_u32_e32 v10, 0x3000, v161
	ds_write2_b32 v10, v8, v9 offset0:56 offset1:124
	ds_read_b128 v[8:11], v60 offset:224
	ds_read_b128 v[12:15], v60 offset:240
	ds_read_b128 v[16:19], v61 offset:224
	ds_read_b128 v[20:23], v61 offset:240
	v_lshlrev_b32_e32 v25, 16, v4
	v_lshlrev_b32_e32 v24, 16, v0
	v_and_b32_e32 v27, 0xffff0000, v4
	v_and_b32_e32 v26, 0xffff0000, v0
	v_pk_fma_f32 v[24:25], v[56:57], s[44:45], v[24:25] op_sel_hi:[1,0,1] neg_lo:[1,0,0] neg_hi:[1,0,0]
	v_pk_fma_f32 v[26:27], v[56:57], s[44:45], v[26:27] op_sel_hi:[1,0,1] neg_lo:[1,0,0] neg_hi:[1,0,0]
	v_pk_mul_f32 v[24:25], v[24:25], v[58:59]
	v_pk_mul_f32 v[26:27], v[26:27], v[58:59]
	s_waitcnt lgkmcnt(1)
	v_pk_fma_f32 v[24:25], v[24:25], v[8:9], v[16:17] op_sel_hi:[1,0,0]
	v_pk_fma_f32 v[8:9], v[26:27], v[8:9], v[16:17] op_sel:[0,1,1]
	v_cvt_pk_bf16_f32 v0, v24, v25
	v_cvt_pk_bf16_f32 v4, v8, v9
	v_add_u32_e32 v8, 0x3600, v161
	ds_write2_b32 v8, v0, v4 offset0:80 offset1:148
	v_lshlrev_b32_e32 v9, 16, v5
	v_lshlrev_b32_e32 v8, 16, v1
	v_pk_fma_f32 v[8:9], v[56:57], s[44:45], v[8:9] op_sel_hi:[1,0,1] neg_lo:[1,0,0] neg_hi:[1,0,0]
	v_and_b32_e32 v5, 0xffff0000, v5
	v_and_b32_e32 v4, 0xffff0000, v1
	v_pk_mul_f32 v[8:9], v[8:9], v[58:59]
	v_pk_fma_f32 v[0:1], v[56:57], s[44:45], v[4:5] op_sel_hi:[1,0,1] neg_lo:[1,0,0] neg_hi:[1,0,0]
	v_pk_fma_f32 v[8:9], v[8:9], v[10:11], v[18:19] op_sel_hi:[1,0,0]
	v_pk_mul_f32 v[0:1], v[0:1], v[58:59]
	v_mov_b32_e32 v4, v11
	v_mov_b32_e32 v10, v19
	v_pk_fma_f32 v[0:1], v[0:1], v[4:5], v[10:11] op_sel_hi:[1,0,0]
	v_cvt_pk_bf16_f32 v4, v8, v9
	v_cvt_pk_bf16_f32 v0, v0, v1
	v_add_u32_e32 v1, 0x3800, v161
	ds_write2_b32 v1, v4, v0 offset0:88 offset1:156
	v_lshlrev_b32_e32 v1, 16, v6
	v_lshlrev_b32_e32 v0, 16, v2
	v_and_b32_e32 v5, 0xffff0000, v6
	v_and_b32_e32 v4, 0xffff0000, v2
	v_pk_fma_f32 v[0:1], v[56:57], s[44:45], v[0:1] op_sel_hi:[1,0,1] neg_lo:[1,0,0] neg_hi:[1,0,0]
	v_pk_fma_f32 v[4:5], v[56:57], s[44:45], v[4:5] op_sel_hi:[1,0,1] neg_lo:[1,0,0] neg_hi:[1,0,0]
	v_pk_mul_f32 v[0:1], v[0:1], v[58:59]
	v_pk_mul_f32 v[4:5], v[4:5], v[58:59]
	s_waitcnt lgkmcnt(2)
	v_pk_fma_f32 v[0:1], v[0:1], v[12:13], v[20:21] op_sel_hi:[1,0,0]
	v_pk_fma_f32 v[4:5], v[4:5], v[12:13], v[20:21] op_sel:[0,1,1]
	v_cvt_pk_bf16_f32 v0, v0, v1
	v_cvt_pk_bf16_f32 v1, v4, v5
	v_add_u32_e32 v2, 0x3e00, v161
	ds_write2_b32 v2, v0, v1 offset0:112 offset1:180
	v_lshlrev_b32_e32 v1, 16, v7
	v_lshlrev_b32_e32 v0, 16, v3
	v_and_b32_e32 v5, 0xffff0000, v7
	v_and_b32_e32 v4, 0xffff0000, v3
	v_pk_fma_f32 v[0:1], v[56:57], s[44:45], v[0:1] op_sel_hi:[1,0,1] neg_lo:[1,0,0] neg_hi:[1,0,0]
	v_pk_fma_f32 v[2:3], v[56:57], s[44:45], v[4:5] op_sel_hi:[1,0,1] neg_lo:[1,0,0] neg_hi:[1,0,0]
	v_pk_mul_f32 v[0:1], v[0:1], v[58:59]
	v_pk_mul_f32 v[2:3], v[2:3], v[58:59]
	v_mov_b32_e32 v4, v15
	v_mov_b32_e32 v6, v23
	v_pk_fma_f32 v[0:1], v[0:1], v[14:15], v[22:23] op_sel_hi:[1,0,0]
	v_pk_fma_f32 v[2:3], v[2:3], v[4:5], v[6:7] op_sel_hi:[1,0,0]
	v_cvt_pk_bf16_f32 v0, v0, v1
	v_cvt_pk_bf16_f32 v1, v2, v3
	v_add_u32_e32 v2, 0x4000, v161
	ds_write2_b32 v2, v0, v1 offset0:120 offset1:188
	v_add_u32_e32 v0, v163, v169
	ds_read_b128 v[100:103], v0
	ds_read_b128 v[96:99], v0 offset:32
	ds_read_b128 v[92:95], v0 offset:64
	ds_read_b128 v[88:91], v0 offset:96
	ds_read_b128 v[84:87], v0 offset:128
	ds_read_b128 v[80:83], v0 offset:160
	ds_read_b128 v[72:75], v0 offset:192
	ds_read_b128 v[64:67], v0 offset:224
	v_add_u32_e32 v0, v163, v171
	v_or_b32_e32 v1, s20, v167
	ds_read_b128 v[124:127], v0
	ds_read_b128 v[120:123], v0 offset:32
	ds_read_b128 v[116:119], v0 offset:64
	ds_read_b128 v[112:115], v0 offset:96
	ds_read_b128 v[108:111], v0 offset:128
	ds_read_b128 v[104:107], v0 offset:160
	ds_read_b128 v[76:79], v0 offset:192
	ds_read_b128 v[68:71], v0 offset:224
	v_or_b32_e32 v0, s19, v157
	v_lshlrev_b32_e32 v192, 1, v1
	v_lshl_add_u64 v[206:207], s[36:37], 0, v[192:193]
	v_lshl_add_u64 v[204:205], s[80:81], 0, v[192:193]
	v_lshl_add_u64 v[202:203], s[4:5], 0, v[192:193]
	v_lshlrev_b32_e32 v192, 8, v0
	v_lshl_add_u64 v[128:129], v[158:159], 0, v[192:193]
	global_load_dwordx4 v[0:3], v[128:129], off
	global_load_dwordx4 v[32:35], v[128:129], off offset:32
	v_add_co_u32_e32 v4, vcc, s57, v128
	v_readlane_b32 s20, v253, 61
	s_nop 0
	v_addc_co_u32_e32 v5, vcc, 0, v129, vcc
	global_load_dwordx4 v[36:39], v[4:5], off
	global_load_dwordx4 v[130:133], v[4:5], off offset:32
	global_load_dwordx4 v[134:137], v[4:5], off offset:64
	global_load_dwordx4 v[138:141], v[4:5], off offset:96
	v_readlane_b32 s21, v253, 62
	s_waitcnt vmcnt(3) lgkmcnt(14)
	v_mfma_f32_32x32x16_bf16 v[48:63], v[100:103], v[36:39], 0
	v_and_b32_e32 v4, 0xffff0000, v0
	v_cndmask_b32_e64 v4, v0, v4, s[52:53]
	v_and_b32_e32 v4, 0xffff, v4
	v_cndmask_b32_e64 v0, v4, v0, s[20:21]
	v_readlane_b32 s20, v253, 59
	v_and_b32_e32 v4, 0xffff0000, v1
	v_readlane_b32 s21, v253, 60
	v_and_b32_e32 v40, 0xffff0000, v32
	s_waitcnt vmcnt(2)
	v_mfma_f32_32x32x16_bf16 v[48:63], v[96:99], v[130:133], v[48:63]
	v_cndmask_b32_e64 v1, v1, v4, s[20:21]
	v_readlane_b32 s20, v253, 57
	v_and_b32_e32 v4, 0xffff, v1
	v_readlane_b32 s21, v253, 58
	s_nop 1
	v_cndmask_b32_e64 v1, v1, v4, s[20:21]
	v_readlane_b32 s20, v253, 55
	v_and_b32_e32 v4, 0xffff0000, v2
	v_readlane_b32 s21, v253, 56
	s_nop 1
	v_cndmask_b32_e64 v2, v2, v4, s[20:21]
	v_readlane_b32 s20, v253, 53
	v_and_b32_e32 v4, 0xffff, v2
	v_readlane_b32 s21, v253, 54
	s_nop 1
	v_cndmask_b32_e64 v2, v2, v4, s[20:21]
	v_readlane_b32 s20, v254, 13
	v_readlane_b32 s21, v254, 14
	v_and_b32_e32 v4, 0xffff0000, v3
	v_cndmask_b32_e64 v3, v3, v4, s[86:87]
	v_cndmask_b32_e64 v32, v32, v40, s[20:21]
	v_readlane_b32 s20, v254, 11
	v_and_b32_e32 v40, 0xffff, v32
	v_readlane_b32 s21, v254, 12
	v_and_b32_e32 v4, 0xffff, v3
	v_cndmask_b32_e64 v3, v3, v4, s[84:85]
	v_cndmask_b32_e64 v32, v32, v40, s[20:21]
	v_readlane_b32 s20, v254, 9
	v_and_b32_e32 v40, 0xffff0000, v33
	v_readlane_b32 s21, v254, 10
	v_mfma_f32_32x32x16_bf16 v[16:31], v[100:103], v[0:3], 0
	s_nop 0
	v_cndmask_b32_e64 v33, v33, v40, s[20:21]
	v_readlane_b32 s20, v254, 7
	v_and_b32_e32 v40, 0xffff, v33
	v_readlane_b32 s21, v254, 8
	s_nop 1
	v_cndmask_b32_e64 v33, v33, v40, s[20:21]
	v_readlane_b32 s20, v254, 5
	s_waitcnt lgkmcnt(7)
	v_mfma_f32_32x32x16_bf16 v[0:15], v[124:127], v[0:3], 0
	v_and_b32_e32 v40, 0xffff0000, v34
	v_readlane_b32 s21, v254, 6
	s_nop 1
	v_cndmask_b32_e64 v34, v34, v40, s[20:21]
	v_readlane_b32 s20, v254, 3
	v_and_b32_e32 v40, 0xffff, v34
	v_readlane_b32 s21, v254, 4
	s_nop 1
	v_cndmask_b32_e64 v34, v34, v40, s[20:21]
	v_readlane_b32 s20, v254, 1
	v_and_b32_e32 v40, 0xffff0000, v35
	v_readlane_b32 s21, v254, 2
	s_nop 1
	v_cndmask_b32_e64 v35, v35, v40, s[20:21]
	v_readlane_b32 s20, v253, 63
	v_and_b32_e32 v40, 0xffff, v35
	v_readlane_b32 s21, v254, 0
	s_nop 1
	v_cndmask_b32_e64 v35, v35, v40, s[20:21]
	v_readlane_b32 s20, v254, 29
	v_readlane_b32 s21, v254, 30
	v_mfma_f32_32x32x16_bf16 v[16:31], v[96:99], v[32:35], v[16:31]
	s_waitcnt lgkmcnt(6)
	v_mfma_f32_32x32x16_bf16 v[0:15], v[120:123], v[32:35], v[0:15]
	s_nop 9
	ds_write_b128 v175, v[16:19]
	ds_write_b128 v175, v[20:23] offset:16
	ds_write_b128 v175, v[24:27] offset:32
	ds_write_b128 v175, v[28:31] offset:48
	ds_write_b128 v175, v[0:3] offset:128
	ds_write_b128 v175, v[4:7] offset:144
	ds_write_b128 v175, v[8:11] offset:160
	ds_write_b128 v175, v[12:15] offset:176
	v_or_b32_e32 v8, s19, v160
	v_lshlrev_b32_e32 v179, 2, v8
	v_lshlrev_b64 v[8:9], 11, v[154:155]
	v_mfma_f32_32x32x16_bf16 v[32:47], v[124:127], v[36:39], 0
	v_lshl_add_u64 v[10:11], v[206:207], 0, v[8:9]
	v_lshl_add_u64 v[8:9], v[204:205], 0, v[8:9]
	v_mfma_f32_32x32x16_bf16 v[32:47], v[120:123], v[130:133], v[32:47]
	s_waitcnt vmcnt(1)
	v_and_b32_e32 v130, 0xffff0000, v134
	v_cndmask_b32_e64 v130, v134, v130, s[20:21]
	v_readlane_b32 s20, v254, 27
	v_and_b32_e32 v131, 0xffff, v130
	v_readlane_b32 s21, v254, 28
	s_nop 1
	v_cndmask_b32_e64 v130, v130, v131, s[20:21]
	v_readlane_b32 s20, v254, 25
	v_and_b32_e32 v131, 0xffff0000, v135
	v_readlane_b32 s21, v254, 26
	s_nop 1
	v_cndmask_b32_e64 v131, v135, v131, s[20:21]
	v_readlane_b32 s20, v254, 23
	v_and_b32_e32 v132, 0xffff, v131
	v_readlane_b32 s21, v254, 24
	s_nop 1
	v_cndmask_b32_e64 v131, v131, v132, s[20:21]
	v_readlane_b32 s20, v254, 21
	v_and_b32_e32 v132, 0xffff0000, v136
	v_readlane_b32 s21, v254, 22
	s_nop 1
	v_cndmask_b32_e64 v132, v136, v132, s[20:21]
	v_readlane_b32 s20, v254, 19
	v_and_b32_e32 v133, 0xffff, v132
	v_readlane_b32 s21, v254, 20
	v_or_b32_e32 v136, s14, v172
	s_nop 0
	v_cndmask_b32_e64 v132, v132, v133, s[20:21]
	v_readlane_b32 s20, v254, 17
	v_and_b32_e32 v133, 0xffff0000, v137
	v_readlane_b32 s21, v254, 18
	s_nop 1
	v_cndmask_b32_e64 v133, v137, v133, s[20:21]
	v_readlane_b32 s20, v254, 15
	v_and_b32_e32 v134, 0xffff, v133
	v_readlane_b32 s21, v254, 16
	v_mov_b32_e32 v137, s15
	s_nop 0
	v_cndmask_b32_e64 v133, v133, v134, s[20:21]
	v_readlane_b32 s20, v254, 45
	v_readlane_b32 s21, v254, 46
	v_mfma_f32_32x32x16_bf16 v[48:63], v[92:95], v[130:133], v[48:63]
	s_waitcnt lgkmcnt(13)
	v_mfma_f32_32x32x16_bf16 v[32:47], v[116:119], v[130:133], v[32:47]
	s_waitcnt vmcnt(0)
	v_and_b32_e32 v130, 0xffff0000, v138
	v_cndmask_b32_e64 v130, v138, v130, s[20:21]
	v_readlane_b32 s20, v254, 43
	v_and_b32_e32 v131, 0xffff, v130
	v_readlane_b32 s21, v254, 44
	s_nop 1
	v_cndmask_b32_e64 v130, v130, v131, s[20:21]
	v_readlane_b32 s20, v254, 41
	v_and_b32_e32 v131, 0xffff0000, v139
	v_readlane_b32 s21, v254, 42
	s_nop 1
	v_cndmask_b32_e64 v131, v139, v131, s[20:21]
	v_readlane_b32 s20, v254, 39
	v_and_b32_e32 v132, 0xffff, v131
	v_readlane_b32 s21, v254, 40
	s_nop 1
	v_cndmask_b32_e64 v131, v131, v132, s[20:21]
	v_readlane_b32 s20, v254, 37
	v_and_b32_e32 v132, 0xffff0000, v140
	v_readlane_b32 s21, v254, 38
	s_nop 1
	v_cndmask_b32_e64 v132, v140, v132, s[20:21]
	v_readlane_b32 s20, v254, 35
	v_and_b32_e32 v133, 0xffff, v132
	v_readlane_b32 s21, v254, 36
	v_or_b32_e32 v140, s14, v170
	s_nop 0
	v_cndmask_b32_e64 v132, v132, v133, s[20:21]
	v_readlane_b32 s20, v254, 33
	v_and_b32_e32 v133, 0xffff0000, v141
	v_readlane_b32 s21, v254, 34
	s_nop 1
	v_cndmask_b32_e64 v133, v141, v133, s[20:21]
	v_readlane_b32 s20, v254, 31
	v_and_b32_e32 v134, 0xffff, v133
	v_readlane_b32 s21, v254, 32
	v_mov_b32_e32 v141, s15
	s_nop 0
	v_cndmask_b32_e64 v133, v133, v134, s[20:21]
	v_readlane_b32 s20, v254, 59
	v_readlane_b32 s21, v254, 60
	v_mfma_f32_32x32x16_bf16 v[48:63], v[88:91], v[130:133], v[48:63]
	s_waitcnt lgkmcnt(12)
	v_mfma_f32_32x32x16_bf16 v[32:47], v[112:115], v[130:133], v[32:47]
	v_mov_b32_e32 v131, s15
	v_or_b32_e32 v130, s14, v160
	v_lshlrev_b64 v[0:1], 11, v[130:131]
	s_nop 6
	ds_write_b128 v177, v[48:51]
	ds_write_b128 v177, v[52:55] offset:16
	ds_write_b128 v177, v[56:59] offset:32
	ds_write_b128 v177, v[60:63] offset:48
	ds_write_b128 v177, v[32:35] offset:128
	ds_write_b128 v177, v[36:39] offset:144
	ds_write_b128 v177, v[40:43] offset:160
	ds_write_b128 v177, v[44:47] offset:176
	v_lshl_add_u64 v[2:3], v[206:207], 0, v[0:1]
	v_lshl_add_u64 v[0:1], v[204:205], 0, v[0:1]
	global_load_dwordx4 v[4:7], v[2:3], off nt
	global_load_dword v208, v179, s[12:13]
	global_load_dwordx4 v[52:55], v[10:11], off nt
	v_mov_b32_e32 v133, s15
	global_load_dwordx4 v[0:3], v[0:1], off nt
	s_nop 0
	global_load_dwordx4 v[48:51], v[8:9], off nt
	global_load_dword v192, v179, s[12:13] offset:32
	v_lshlrev_b64 v[8:9], 11, v[150:151]
	v_lshl_add_u64 v[10:11], v[206:207], 0, v[8:9]
	v_lshl_add_u64 v[8:9], v[204:205], 0, v[8:9]
	global_load_dwordx4 v[44:47], v[10:11], off nt
	global_load_dwordx4 v[40:43], v[8:9], off nt
	global_load_dword v152, v179, s[12:13] offset:64
	v_lshlrev_b64 v[8:9], 11, v[146:147]
	v_lshl_add_u64 v[10:11], v[206:207], 0, v[8:9]
	v_lshl_add_u64 v[8:9], v[204:205], 0, v[8:9]
	global_load_dwordx4 v[36:39], v[10:11], off nt
	global_load_dwordx4 v[32:35], v[8:9], off nt
	global_load_dword v148, v179, s[12:13] offset:96
	v_lshlrev_b64 v[8:9], 11, v[140:141]
	v_lshl_add_u64 v[10:11], v[206:207], 0, v[8:9]
	v_lshl_add_u64 v[8:9], v[204:205], 0, v[8:9]
	global_load_dwordx4 v[28:31], v[10:11], off nt
	global_load_dwordx4 v[24:27], v[8:9], off nt
	global_load_dword v142, v179, s[12:13] offset:128
	v_lshlrev_b64 v[8:9], 11, v[136:137]
	v_lshl_add_u64 v[10:11], v[206:207], 0, v[8:9]
	v_lshl_add_u64 v[8:9], v[204:205], 0, v[8:9]
	v_or_b32_e32 v132, s14, v174
	global_load_dwordx4 v[20:23], v[10:11], off nt
	global_load_dwordx4 v[16:19], v[8:9], off nt
	global_load_dword v138, v179, s[12:13] offset:160
	v_lshlrev_b64 v[8:9], 11, v[132:133]
	v_lshlrev_b64 v[60:61], 11, v[144:145]
	v_lshl_add_u64 v[10:11], v[206:207], 0, v[8:9]
	v_lshl_add_u64 v[8:9], v[204:205], 0, v[8:9]
	v_lshl_add_u64 v[56:57], v[206:207], 0, v[60:61]
	v_lshl_add_u64 v[60:61], v[204:205], 0, v[60:61]
	global_load_dwordx4 v[12:15], v[10:11], off nt
	s_nop 0
	global_load_dwordx4 v[8:11], v[8:9], off nt
	s_nop 0
	global_load_dword v134, v179, s[12:13] offset:192
	s_nop 0
	global_load_dwordx4 v[56:59], v[56:57], off nt
	s_nop 0
	global_load_dwordx4 v[60:63], v[60:61], off nt
	s_nop 0
	global_load_dword v210, v179, s[12:13] offset:224
	s_waitcnt vmcnt(1)
	ds_read_b128 v[212:215], v173
	ds_read_b128 v[216:219], v173 offset:16
	v_lshlrev_b32_e32 v196, 16, v4
	v_and_b32_e32 v197, 0xffff0000, v4
	v_lshlrev_b32_e32 v4, 16, v5
	s_waitcnt lgkmcnt(1)
	v_pk_add_f32 v[212:213], v[208:209], v[212:213] op_sel_hi:[0,1]
	v_pk_mul_f32 v[196:197], v[212:213], v[196:197]
	v_lshlrev_b32_e32 v212, 16, v0
	v_and_b32_e32 v213, 0xffff0000, v0
	v_pk_mul_f32 v[196:197], v[196:197], v[212:213]
	v_and_b32_e32 v5, 0xffff0000, v5
	v_cvt_pk_bf16_f32 v0, v196, v197
	v_pk_add_f32 v[196:197], v[208:209], v[214:215] op_sel_hi:[0,1]
	v_pk_mul_f32 v[4:5], v[196:197], v[4:5]
	v_lshlrev_b32_e32 v196, 16, v1
	v_and_b32_e32 v197, 0xffff0000, v1
	v_pk_mul_f32 v[4:5], v[4:5], v[196:197]
	s_waitcnt lgkmcnt(0)
	v_pk_add_f32 v[196:197], v[208:209], v[216:217] op_sel_hi:[0,1]
	v_cvt_pk_bf16_f32 v1, v4, v5
	v_lshlrev_b32_e32 v4, 16, v6
	v_and_b32_e32 v5, 0xffff0000, v6
	v_pk_mul_f32 v[4:5], v[196:197], v[4:5]
	v_lshlrev_b32_e32 v196, 16, v2
	v_and_b32_e32 v197, 0xffff0000, v2
	v_pk_mul_f32 v[4:5], v[4:5], v[196:197]
	s_nop 0
	v_cvt_pk_bf16_f32 v2, v4, v5
	v_lshlrev_b32_e32 v4, 16, v7
	v_and_b32_e32 v5, 0xffff0000, v7
	v_pk_add_f32 v[6:7], v[208:209], v[218:219] op_sel_hi:[0,1]
	v_pk_mul_f32 v[4:5], v[6:7], v[4:5]
	v_lshlrev_b32_e32 v6, 16, v3
	v_and_b32_e32 v7, 0xffff0000, v3
	v_pk_mul_f32 v[4:5], v[4:5], v[6:7]
	s_nop 0
	v_cvt_pk_bf16_f32 v3, v4, v5
	v_lshlrev_b64 v[4:5], 12, v[130:131]
	v_lshl_add_u64 v[4:5], v[202:203], 0, v[4:5]
	global_store_dwordx4 v[4:5], v[0:3], off
	ds_read_b128 v[0:3], v173 offset:2176
	ds_read_b128 v[4:7], v173 offset:2192
	v_lshlrev_b32_e32 v130, 16, v52
	v_and_b32_e32 v131, 0xffff0000, v52
	v_lshlrev_b32_e32 v52, 16, v53
	s_waitcnt lgkmcnt(1)
	v_pk_add_f32 v[0:1], v[192:193], v[0:1] op_sel_hi:[0,1]
	v_and_b32_e32 v53, 0xffff0000, v53
	v_pk_add_f32 v[2:3], v[192:193], v[2:3] op_sel_hi:[0,1]
	v_pk_mul_f32 v[0:1], v[0:1], v[130:131]
	v_lshlrev_b32_e32 v130, 16, v48
	v_and_b32_e32 v131, 0xffff0000, v48
	v_pk_mul_f32 v[2:3], v[2:3], v[52:53]
	v_lshlrev_b32_e32 v48, 16, v49
	v_and_b32_e32 v49, 0xffff0000, v49
	v_pk_mul_f32 v[0:1], v[0:1], v[130:131]
	v_pk_mul_f32 v[2:3], v[2:3], v[48:49]
	v_cvt_pk_bf16_f32 v0, v0, v1
	v_cvt_pk_bf16_f32 v1, v2, v3
	v_lshlrev_b32_e32 v2, 16, v54
	v_and_b32_e32 v3, 0xffff0000, v54
	s_waitcnt lgkmcnt(0)
	v_pk_add_f32 v[4:5], v[192:193], v[4:5] op_sel_hi:[0,1]
	v_pk_mul_f32 v[2:3], v[4:5], v[2:3]
	v_lshlrev_b32_e32 v4, 16, v50
	v_and_b32_e32 v5, 0xffff0000, v50
	v_pk_mul_f32 v[2:3], v[2:3], v[4:5]
	v_lshlrev_b32_e32 v4, 16, v55
	v_and_b32_e32 v5, 0xffff0000, v55
	v_pk_add_f32 v[6:7], v[192:193], v[6:7] op_sel_hi:[0,1]
	v_pk_mul_f32 v[4:5], v[6:7], v[4:5]
	v_lshlrev_b32_e32 v6, 16, v51
	v_and_b32_e32 v7, 0xffff0000, v51
	v_pk_mul_f32 v[4:5], v[4:5], v[6:7]
	v_cvt_pk_bf16_f32 v2, v2, v3
	v_cvt_pk_bf16_f32 v3, v4, v5
	v_lshlrev_b64 v[4:5], 12, v[154:155]
	v_lshl_add_u64 v[4:5], v[202:203], 0, v[4:5]
	global_store_dwordx4 v[4:5], v[0:3], off
	ds_read_b128 v[0:3], v173 offset:4352
	ds_read_b128 v[4:7], v173 offset:4368
	v_lshlrev_b32_e32 v48, 16, v44
	v_and_b32_e32 v49, 0xffff0000, v44
	v_lshlrev_b32_e32 v44, 16, v45
	s_waitcnt lgkmcnt(1)
	v_pk_add_f32 v[0:1], v[152:153], v[0:1] op_sel_hi:[0,1]
	v_and_b32_e32 v45, 0xffff0000, v45
	v_pk_add_f32 v[2:3], v[152:153], v[2:3] op_sel_hi:[0,1]
	v_pk_mul_f32 v[0:1], v[0:1], v[48:49]
	v_lshlrev_b32_e32 v48, 16, v40
	v_and_b32_e32 v49, 0xffff0000, v40
	v_pk_mul_f32 v[2:3], v[2:3], v[44:45]
	v_lshlrev_b32_e32 v40, 16, v41
	v_and_b32_e32 v41, 0xffff0000, v41
	v_pk_mul_f32 v[0:1], v[0:1], v[48:49]
	v_pk_mul_f32 v[2:3], v[2:3], v[40:41]
	v_cvt_pk_bf16_f32 v0, v0, v1
	v_cvt_pk_bf16_f32 v1, v2, v3
	v_lshlrev_b32_e32 v2, 16, v46
	v_and_b32_e32 v3, 0xffff0000, v46
	s_waitcnt lgkmcnt(0)
	v_pk_add_f32 v[4:5], v[152:153], v[4:5] op_sel_hi:[0,1]
	v_pk_mul_f32 v[2:3], v[4:5], v[2:3]
	v_lshlrev_b32_e32 v4, 16, v42
	v_and_b32_e32 v5, 0xffff0000, v42
	v_pk_mul_f32 v[2:3], v[2:3], v[4:5]
	v_lshlrev_b32_e32 v4, 16, v47
	v_and_b32_e32 v5, 0xffff0000, v47
	v_pk_add_f32 v[6:7], v[152:153], v[6:7] op_sel_hi:[0,1]
	v_pk_mul_f32 v[4:5], v[6:7], v[4:5]
	v_lshlrev_b32_e32 v6, 16, v43
	v_and_b32_e32 v7, 0xffff0000, v43
	v_pk_mul_f32 v[4:5], v[4:5], v[6:7]
	v_cvt_pk_bf16_f32 v2, v2, v3
	v_cvt_pk_bf16_f32 v3, v4, v5
	v_lshlrev_b64 v[4:5], 12, v[150:151]
	v_lshl_add_u64 v[4:5], v[202:203], 0, v[4:5]
	global_store_dwordx4 v[4:5], v[0:3], off
	ds_read_b128 v[0:3], v173 offset:6528
	ds_read_b128 v[4:7], v173 offset:6544
	v_lshlrev_b32_e32 v40, 16, v36
	v_and_b32_e32 v41, 0xffff0000, v36
	v_lshlrev_b32_e32 v36, 16, v37
	s_waitcnt lgkmcnt(1)
	v_pk_add_f32 v[0:1], v[148:149], v[0:1] op_sel_hi:[0,1]
	v_and_b32_e32 v37, 0xffff0000, v37
	v_pk_add_f32 v[2:3], v[148:149], v[2:3] op_sel_hi:[0,1]
	v_pk_mul_f32 v[0:1], v[0:1], v[40:41]
	v_lshlrev_b32_e32 v40, 16, v32
	v_and_b32_e32 v41, 0xffff0000, v32
	v_pk_mul_f32 v[2:3], v[2:3], v[36:37]
	v_lshlrev_b32_e32 v32, 16, v33
	v_and_b32_e32 v33, 0xffff0000, v33
	v_pk_mul_f32 v[0:1], v[0:1], v[40:41]
	v_pk_mul_f32 v[2:3], v[2:3], v[32:33]
	v_cvt_pk_bf16_f32 v0, v0, v1
	v_cvt_pk_bf16_f32 v1, v2, v3
	v_lshlrev_b32_e32 v2, 16, v38
	v_and_b32_e32 v3, 0xffff0000, v38
	s_waitcnt lgkmcnt(0)
	v_pk_add_f32 v[4:5], v[148:149], v[4:5] op_sel_hi:[0,1]
	v_pk_mul_f32 v[2:3], v[4:5], v[2:3]
	v_lshlrev_b32_e32 v4, 16, v34
	v_and_b32_e32 v5, 0xffff0000, v34
	v_pk_mul_f32 v[2:3], v[2:3], v[4:5]
	v_lshlrev_b32_e32 v4, 16, v39
	v_and_b32_e32 v5, 0xffff0000, v39
	v_pk_add_f32 v[6:7], v[148:149], v[6:7] op_sel_hi:[0,1]
	v_pk_mul_f32 v[4:5], v[6:7], v[4:5]
	v_lshlrev_b32_e32 v6, 16, v35
	v_and_b32_e32 v7, 0xffff0000, v35
	v_pk_mul_f32 v[4:5], v[4:5], v[6:7]
	v_cvt_pk_bf16_f32 v2, v2, v3
	v_cvt_pk_bf16_f32 v3, v4, v5
	v_lshlrev_b64 v[4:5], 12, v[146:147]
	v_lshl_add_u64 v[4:5], v[202:203], 0, v[4:5]
	global_store_dwordx4 v[4:5], v[0:3], off
	ds_read_b128 v[0:3], v173 offset:8704
	ds_read_b128 v[4:7], v173 offset:8720
	v_lshlrev_b32_e32 v32, 16, v28
	v_and_b32_e32 v33, 0xffff0000, v28
	v_lshlrev_b32_e32 v28, 16, v29
	s_waitcnt lgkmcnt(1)
	v_pk_add_f32 v[0:1], v[142:143], v[0:1] op_sel_hi:[0,1]
	v_and_b32_e32 v29, 0xffff0000, v29
	v_pk_add_f32 v[2:3], v[142:143], v[2:3] op_sel_hi:[0,1]
	v_pk_mul_f32 v[0:1], v[0:1], v[32:33]
	v_lshlrev_b32_e32 v32, 16, v24
	v_and_b32_e32 v33, 0xffff0000, v24
	v_pk_mul_f32 v[2:3], v[2:3], v[28:29]
	v_lshlrev_b32_e32 v24, 16, v25
	v_and_b32_e32 v25, 0xffff0000, v25
	v_pk_mul_f32 v[0:1], v[0:1], v[32:33]
	v_pk_mul_f32 v[2:3], v[2:3], v[24:25]
	v_cvt_pk_bf16_f32 v0, v0, v1
	v_cvt_pk_bf16_f32 v1, v2, v3
	v_lshlrev_b32_e32 v2, 16, v30
	v_and_b32_e32 v3, 0xffff0000, v30
	s_waitcnt lgkmcnt(0)
	v_pk_add_f32 v[4:5], v[142:143], v[4:5] op_sel_hi:[0,1]
	v_pk_mul_f32 v[2:3], v[4:5], v[2:3]
	v_lshlrev_b32_e32 v4, 16, v26
	v_and_b32_e32 v5, 0xffff0000, v26
	v_pk_mul_f32 v[2:3], v[2:3], v[4:5]
	v_lshlrev_b32_e32 v4, 16, v31
	v_and_b32_e32 v5, 0xffff0000, v31
	v_pk_add_f32 v[6:7], v[142:143], v[6:7] op_sel_hi:[0,1]
	v_pk_mul_f32 v[4:5], v[6:7], v[4:5]
	v_lshlrev_b32_e32 v6, 16, v27
	v_and_b32_e32 v7, 0xffff0000, v27
	v_pk_mul_f32 v[4:5], v[4:5], v[6:7]
	v_cvt_pk_bf16_f32 v2, v2, v3
	v_cvt_pk_bf16_f32 v3, v4, v5
	v_lshlrev_b64 v[4:5], 12, v[140:141]
	v_lshl_add_u64 v[4:5], v[202:203], 0, v[4:5]
	global_store_dwordx4 v[4:5], v[0:3], off
	ds_read_b128 v[0:3], v173 offset:10880
	ds_read_b128 v[4:7], v173 offset:10896
	v_lshlrev_b32_e32 v24, 16, v20
	v_and_b32_e32 v25, 0xffff0000, v20
	v_lshlrev_b32_e32 v20, 16, v21
	s_waitcnt lgkmcnt(1)
	v_pk_add_f32 v[0:1], v[138:139], v[0:1] op_sel_hi:[0,1]
	v_and_b32_e32 v21, 0xffff0000, v21
	v_pk_add_f32 v[2:3], v[138:139], v[2:3] op_sel_hi:[0,1]
	v_pk_mul_f32 v[0:1], v[0:1], v[24:25]
	v_lshlrev_b32_e32 v24, 16, v16
	v_and_b32_e32 v25, 0xffff0000, v16
	v_pk_mul_f32 v[2:3], v[2:3], v[20:21]
	v_lshlrev_b32_e32 v16, 16, v17
	v_and_b32_e32 v17, 0xffff0000, v17
	v_pk_mul_f32 v[0:1], v[0:1], v[24:25]
	v_pk_mul_f32 v[2:3], v[2:3], v[16:17]
	v_cvt_pk_bf16_f32 v0, v0, v1
	v_cvt_pk_bf16_f32 v1, v2, v3
	v_lshlrev_b32_e32 v2, 16, v22
	v_and_b32_e32 v3, 0xffff0000, v22
	s_waitcnt lgkmcnt(0)
	v_pk_add_f32 v[4:5], v[138:139], v[4:5] op_sel_hi:[0,1]
	v_pk_mul_f32 v[2:3], v[4:5], v[2:3]
	v_lshlrev_b32_e32 v4, 16, v18
	v_and_b32_e32 v5, 0xffff0000, v18
	v_pk_mul_f32 v[2:3], v[2:3], v[4:5]
	v_lshlrev_b32_e32 v4, 16, v23
	v_and_b32_e32 v5, 0xffff0000, v23
	v_pk_add_f32 v[6:7], v[138:139], v[6:7] op_sel_hi:[0,1]
	v_pk_mul_f32 v[4:5], v[6:7], v[4:5]
	v_lshlrev_b32_e32 v6, 16, v19
	v_and_b32_e32 v7, 0xffff0000, v19
	v_pk_mul_f32 v[4:5], v[4:5], v[6:7]
	v_cvt_pk_bf16_f32 v2, v2, v3
	v_cvt_pk_bf16_f32 v3, v4, v5
	v_lshlrev_b64 v[4:5], 12, v[136:137]
	v_lshl_add_u64 v[4:5], v[202:203], 0, v[4:5]
	global_store_dwordx4 v[4:5], v[0:3], off
	ds_read_b128 v[0:3], v173 offset:13056
	ds_read_b128 v[4:7], v173 offset:13072
	v_lshlrev_b32_e32 v16, 16, v12
	v_and_b32_e32 v17, 0xffff0000, v12
	v_lshlrev_b32_e32 v12, 16, v13
	s_waitcnt lgkmcnt(1)
	v_pk_add_f32 v[0:1], v[134:135], v[0:1] op_sel_hi:[0,1]
	v_and_b32_e32 v13, 0xffff0000, v13
	v_pk_add_f32 v[2:3], v[134:135], v[2:3] op_sel_hi:[0,1]
	v_pk_mul_f32 v[0:1], v[0:1], v[16:17]
	v_lshlrev_b32_e32 v16, 16, v8
	v_and_b32_e32 v17, 0xffff0000, v8
	v_pk_mul_f32 v[2:3], v[2:3], v[12:13]
	v_lshlrev_b32_e32 v8, 16, v9
	v_and_b32_e32 v9, 0xffff0000, v9
	v_pk_mul_f32 v[0:1], v[0:1], v[16:17]
	v_pk_mul_f32 v[2:3], v[2:3], v[8:9]
	v_cvt_pk_bf16_f32 v0, v0, v1
	v_cvt_pk_bf16_f32 v1, v2, v3
	v_lshlrev_b32_e32 v2, 16, v14
	v_and_b32_e32 v3, 0xffff0000, v14
	s_waitcnt lgkmcnt(0)
	v_pk_add_f32 v[4:5], v[134:135], v[4:5] op_sel_hi:[0,1]
	v_pk_mul_f32 v[2:3], v[4:5], v[2:3]
	v_lshlrev_b32_e32 v4, 16, v10
	v_and_b32_e32 v5, 0xffff0000, v10
	v_pk_mul_f32 v[2:3], v[2:3], v[4:5]
	v_lshlrev_b32_e32 v4, 16, v15
	v_and_b32_e32 v5, 0xffff0000, v15
	v_pk_add_f32 v[6:7], v[134:135], v[6:7] op_sel_hi:[0,1]
	v_pk_mul_f32 v[4:5], v[6:7], v[4:5]
	v_lshlrev_b32_e32 v6, 16, v11
	v_and_b32_e32 v7, 0xffff0000, v11
	v_pk_mul_f32 v[4:5], v[4:5], v[6:7]
	v_cvt_pk_bf16_f32 v2, v2, v3
	v_cvt_pk_bf16_f32 v3, v4, v5
	v_lshlrev_b64 v[4:5], 12, v[132:133]
	v_lshl_add_u64 v[4:5], v[202:203], 0, v[4:5]
	global_store_dwordx4 v[4:5], v[0:3], off
	ds_read_b128 v[0:3], v173 offset:15232
	ds_read_b128 v[4:7], v173 offset:15248
	v_lshlrev_b32_e32 v8, 16, v56
	v_and_b32_e32 v9, 0xffff0000, v56
	s_waitcnt vmcnt(7) lgkmcnt(1)
	v_pk_add_f32 v[0:1], v[210:211], v[0:1] op_sel_hi:[0,1]
	v_pk_mul_f32 v[0:1], v[0:1], v[8:9]
	v_lshlrev_b32_e32 v8, 16, v60
	v_and_b32_e32 v9, 0xffff0000, v60
	v_pk_mul_f32 v[0:1], v[0:1], v[8:9]
	v_lshlrev_b32_e32 v8, 16, v57
	v_and_b32_e32 v9, 0xffff0000, v57
	v_pk_add_f32 v[2:3], v[210:211], v[2:3] op_sel_hi:[0,1]
	v_pk_mul_f32 v[2:3], v[2:3], v[8:9]
	v_lshlrev_b32_e32 v8, 16, v61
	v_and_b32_e32 v9, 0xffff0000, v61
	v_pk_mul_f32 v[2:3], v[2:3], v[8:9]
	v_cvt_pk_bf16_f32 v0, v0, v1
	v_cvt_pk_bf16_f32 v1, v2, v3
	v_lshlrev_b32_e32 v2, 16, v58
	v_and_b32_e32 v3, 0xffff0000, v58
	s_waitcnt lgkmcnt(0)
	v_pk_add_f32 v[4:5], v[210:211], v[4:5] op_sel_hi:[0,1]
	v_pk_mul_f32 v[2:3], v[4:5], v[2:3]
	v_lshlrev_b32_e32 v4, 16, v62
	v_and_b32_e32 v5, 0xffff0000, v62
	v_pk_mul_f32 v[2:3], v[2:3], v[4:5]
	v_lshlrev_b32_e32 v4, 16, v59
	v_and_b32_e32 v5, 0xffff0000, v59
	v_pk_add_f32 v[6:7], v[210:211], v[6:7] op_sel_hi:[0,1]
	v_pk_mul_f32 v[4:5], v[6:7], v[4:5]
	v_lshlrev_b32_e32 v6, 16, v63
	v_and_b32_e32 v7, 0xffff0000, v63
	v_pk_mul_f32 v[4:5], v[4:5], v[6:7]
	v_cvt_pk_bf16_f32 v2, v2, v3
	v_cvt_pk_bf16_f32 v3, v4, v5
	v_lshlrev_b64 v[4:5], 12, v[144:145]
	v_lshl_add_u64 v[4:5], v[202:203], 0, v[4:5]
	global_store_dwordx4 v[4:5], v[0:3], off
	v_add_co_u32_e32 v4, vcc, s25, v128
	s_nop 1
	v_addc_co_u32_e32 v5, vcc, 0, v129, vcc
	global_load_dwordx4 v[0:3], v[4:5], off
	global_load_dwordx4 v[52:55], v[4:5], off offset:32
	global_load_dwordx4 v[48:51], v[4:5], off offset:64
	global_load_dwordx4 v[44:47], v[4:5], off offset:96
	global_load_dwordx4 v[40:43], v[4:5], off offset:128
	global_load_dwordx4 v[36:39], v[4:5], off offset:160
	v_add_co_u32_e32 v4, vcc, s99, v128
	s_waitcnt vmcnt(5)
	v_mfma_f32_32x32x16_bf16 v[16:31], v[100:103], v[0:3], 0
	v_addc_co_u32_e32 v5, vcc, 0, v129, vcc
	global_load_dwordx4 v[32:35], v[4:5], off
	global_load_dwordx4 v[152:155], v[4:5], off offset:32
	global_load_dwordx4 v[148:151], v[4:5], off offset:64
	global_load_dwordx4 v[144:147], v[4:5], off offset:96
	global_load_dwordx4 v[140:143], v[4:5], off offset:128
	global_load_dwordx4 v[136:139], v[4:5], off offset:160
	global_load_dwordx4 v[132:135], v[4:5], off offset:192
	global_load_dwordx4 v[128:131], v[4:5], off offset:224
	v_mfma_f32_32x32x16_bf16 v[0:15], v[124:127], v[0:3], 0
	s_waitcnt vmcnt(12)
	v_mfma_f32_32x32x16_bf16 v[16:31], v[96:99], v[52:55], v[16:31]
	v_mfma_f32_32x32x16_bf16 v[0:15], v[120:123], v[52:55], v[0:15]
	s_waitcnt vmcnt(11)
	v_mfma_f32_32x32x16_bf16 v[16:31], v[92:95], v[48:51], v[16:31]
	v_mfma_f32_32x32x16_bf16 v[0:15], v[116:119], v[48:51], v[0:15]
	s_waitcnt vmcnt(10)
	v_mfma_f32_32x32x16_bf16 v[16:31], v[88:91], v[44:47], v[16:31]
	v_mfma_f32_32x32x16_bf16 v[0:15], v[112:115], v[44:47], v[0:15]
	s_waitcnt vmcnt(9)
	v_and_b32_e32 v44, 0xffff0000, v40
	v_cndmask_b32_e64 v40, v40, v44, s[52:53]
	v_and_b32_e32 v44, 0xffff, v40
	v_cndmask_b32_e64 v40, v40, v44, s[20:21]
	v_readlane_b32 s20, v254, 57
	v_and_b32_e32 v44, 0xffff0000, v41
	v_readlane_b32 s21, v254, 58
	s_waitcnt vmcnt(7)
	v_mfma_f32_32x32x16_bf16 v[48:63], v[100:103], v[32:35], 0
	v_cndmask_b32_e64 v41, v41, v44, s[20:21]
	v_readlane_b32 s20, v254, 55
	v_and_b32_e32 v44, 0xffff, v41
	v_readlane_b32 s21, v254, 56
	s_nop 1
	v_cndmask_b32_e64 v41, v41, v44, s[20:21]
	v_readlane_b32 s20, v254, 53
	v_and_b32_e32 v44, 0xffff0000, v42
	v_readlane_b32 s21, v254, 54
	s_waitcnt vmcnt(6)
	v_mfma_f32_32x32x16_bf16 v[48:63], v[96:99], v[152:155], v[48:63]
	v_cndmask_b32_e64 v42, v42, v44, s[20:21]
	v_readlane_b32 s20, v254, 51
	v_and_b32_e32 v44, 0xffff, v42
	v_readlane_b32 s21, v254, 52
	s_nop 1
	v_cndmask_b32_e64 v42, v42, v44, s[20:21]
	v_readlane_b32 s20, v254, 49
	v_and_b32_e32 v44, 0xffff0000, v43
	v_readlane_b32 s21, v254, 50
	s_waitcnt vmcnt(5)
	v_mfma_f32_32x32x16_bf16 v[48:63], v[92:95], v[148:151], v[48:63]
	v_mov_b32_e32 v93, s15
	v_cndmask_b32_e64 v43, v43, v44, s[20:21]
	v_readlane_b32 s20, v254, 47
	v_and_b32_e32 v44, 0xffff, v43
	v_readlane_b32 s21, v254, 48
	v_or_b32_e32 v92, s14, v162
	s_nop 0
	v_cndmask_b32_e64 v43, v43, v44, s[20:21]
	v_readlane_b32 s20, v255, 11
	v_readlane_b32 s21, v255, 12
	v_mfma_f32_32x32x16_bf16 v[16:31], v[84:87], v[40:43], v[16:31]
	v_mfma_f32_32x32x16_bf16 v[0:15], v[108:111], v[40:43], v[0:15]
	v_and_b32_e32 v40, 0xffff0000, v36
	v_cndmask_b32_e64 v36, v36, v40, s[20:21]
	v_readlane_b32 s20, v255, 9
	v_and_b32_e32 v40, 0xffff, v36
	v_readlane_b32 s21, v255, 10
	s_nop 1
	v_cndmask_b32_e64 v36, v36, v40, s[20:21]
	v_readlane_b32 s20, v255, 7
	v_and_b32_e32 v40, 0xffff0000, v37
	v_readlane_b32 s21, v255, 8
	s_waitcnt vmcnt(4)
	v_mfma_f32_32x32x16_bf16 v[48:63], v[88:91], v[144:147], v[48:63]
	v_mov_b32_e32 v89, s15
	v_cndmask_b32_e64 v37, v37, v40, s[20:21]
	v_readlane_b32 s20, v255, 5
	v_and_b32_e32 v40, 0xffff, v37
	v_readlane_b32 s21, v255, 6
	v_or_b32_e32 v88, s14, v178
	s_nop 0
	v_cndmask_b32_e64 v37, v37, v40, s[20:21]
	v_readlane_b32 s20, v255, 3
	v_and_b32_e32 v40, 0xffff0000, v38
	v_readlane_b32 s21, v255, 4
	s_waitcnt vmcnt(3)
	v_mfma_f32_32x32x16_bf16 v[48:63], v[84:87], v[140:143], v[48:63]
	v_mov_b32_e32 v85, s15
	v_cndmask_b32_e64 v38, v38, v40, s[20:21]
	v_readlane_b32 s20, v255, 1
	v_and_b32_e32 v40, 0xffff, v38
	v_readlane_b32 s21, v255, 2
	s_nop 1
	v_cndmask_b32_e64 v38, v38, v40, s[20:21]
	v_readlane_b32 s20, v254, 63
	v_and_b32_e32 v40, 0xffff0000, v39
	v_readlane_b32 s21, v255, 0
	s_waitcnt vmcnt(2)
	v_mfma_f32_32x32x16_bf16 v[48:63], v[80:83], v[136:139], v[48:63]
	v_cndmask_b32_e64 v39, v39, v40, s[20:21]
	v_readlane_b32 s20, v254, 61
	v_and_b32_e32 v40, 0xffff, v39
	v_readlane_b32 s21, v254, 62
	s_nop 1
	v_cndmask_b32_e64 v39, v39, v40, s[20:21]
	v_readlane_b32 s20, v255, 27
	v_readlane_b32 s21, v255, 28
	v_mfma_f32_32x32x16_bf16 v[16:31], v[80:83], v[36:39], v[16:31]
	s_waitcnt vmcnt(1)
	v_and_b32_e32 v80, 0xffff0000, v132
	v_cndmask_b32_e64 v80, v132, v80, s[20:21]
	v_readlane_b32 s20, v255, 25
	v_and_b32_e32 v81, 0xffff, v80
	v_readlane_b32 s21, v255, 26
	v_mfma_f32_32x32x16_bf16 v[0:15], v[104:107], v[36:39], v[0:15]
	s_nop 0
	v_cndmask_b32_e64 v80, v80, v81, s[20:21]
	v_readlane_b32 s20, v255, 23
	v_and_b32_e32 v81, 0xffff0000, v133
	v_readlane_b32 s21, v255, 24
	s_nop 1
	v_cndmask_b32_e64 v81, v133, v81, s[20:21]
	v_mfma_f32_32x32x16_bf16 v[32:47], v[124:127], v[32:35], 0
	v_readlane_b32 s20, v255, 21
	v_and_b32_e32 v82, 0xffff, v81
	v_readlane_b32 s21, v255, 22
	s_nop 1
	v_cndmask_b32_e64 v81, v81, v82, s[20:21]
	v_readlane_b32 s20, v255, 19
	v_mfma_f32_32x32x16_bf16 v[32:47], v[120:123], v[152:155], v[32:47]
	v_and_b32_e32 v82, 0xffff0000, v134
	v_readlane_b32 s21, v255, 20
	s_nop 1
	v_cndmask_b32_e64 v82, v134, v82, s[20:21]
	v_readlane_b32 s20, v255, 17
	v_and_b32_e32 v83, 0xffff, v82
	v_mfma_f32_32x32x16_bf16 v[32:47], v[116:119], v[148:151], v[32:47]
	v_readlane_b32 s21, v255, 18
	s_nop 1
	v_cndmask_b32_e64 v82, v82, v83, s[20:21]
	v_readlane_b32 s20, v255, 15
	v_and_b32_e32 v83, 0xffff0000, v135
	v_readlane_b32 s21, v255, 16
	v_mfma_f32_32x32x16_bf16 v[32:47], v[112:115], v[144:147], v[32:47]
	s_nop 0
	v_cndmask_b32_e64 v83, v135, v83, s[20:21]
	v_readlane_b32 s20, v255, 13
	v_and_b32_e32 v84, 0xffff, v83
	v_readlane_b32 s21, v255, 14
	v_mfma_f32_32x32x16_bf16 v[32:47], v[108:111], v[140:143], v[32:47]
	s_nop 0
	v_cndmask_b32_e64 v83, v83, v84, s[20:21]
	v_readlane_b32 s20, v255, 33
	v_readlane_b32 s21, v255, 34
	v_or_b32_e32 v84, s14, v180
	v_mfma_f32_32x32x16_bf16 v[32:47], v[104:107], v[136:139], v[32:47]
	v_mfma_f32_32x32x16_bf16 v[48:63], v[72:75], v[80:83], v[48:63]
	s_waitcnt vmcnt(0)
	v_and_b32_e32 v72, 0xffff0000, v128
	v_cndmask_b32_e64 v72, v128, v72, s[10:11]
	v_and_b32_e32 v73, 0xffff, v72
	v_cndmask_b32_e64 v72, v72, v73, s[8:9]
	v_and_b32_e32 v73, 0xffff0000, v129
	v_cndmask_b32_e64 v73, v129, v73, s[6:7]
	v_and_b32_e32 v74, 0xffff, v73
	v_mfma_f32_32x32x16_bf16 v[32:47], v[76:79], v[80:83], v[32:47]
	v_cndmask_b32_e64 v73, v73, v74, s[40:41]
	v_and_b32_e32 v74, 0xffff0000, v130
	v_cndmask_b32_e64 v74, v130, v74, s[2:3]
	v_and_b32_e32 v75, 0xffff, v74
	v_cndmask_b32_e64 v74, v74, v75, s[20:21]
	v_readlane_b32 s20, v255, 31
	v_and_b32_e32 v75, 0xffff0000, v131
	v_readlane_b32 s21, v255, 32
	v_mov_b32_e32 v81, s15
	v_or_b32_e32 v80, s14, v182
	v_cndmask_b32_e64 v75, v131, v75, s[20:21]
	v_readlane_b32 s20, v255, 29
	v_and_b32_e32 v76, 0xffff, v75
	v_readlane_b32 s21, v255, 30
	s_nop 1
	v_cndmask_b32_e64 v75, v75, v76, s[20:21]
	s_nop 1
	v_mfma_f32_32x32x16_bf16 v[48:63], v[64:67], v[72:75], v[48:63]
	v_mov_b32_e32 v67, s15
	v_or_b32_e32 v66, s14, v188
	v_mov_b32_e32 v65, s15
	v_or_b32_e32 v64, s14, v190
	v_mfma_f32_32x32x16_bf16 v[32:47], v[68:71], v[72:75], v[32:47]
	ds_write_b128 v175, v[16:19]
	ds_write_b128 v175, v[20:23] offset:16
	ds_write_b128 v175, v[24:27] offset:32
	ds_write_b128 v175, v[28:31] offset:48
	ds_write_b128 v175, v[0:3] offset:128
	ds_write_b128 v175, v[4:7] offset:144
	ds_write_b128 v175, v[8:11] offset:160
	ds_write_b128 v175, v[12:15] offset:176
	ds_write_b128 v177, v[48:51]
	ds_write_b128 v177, v[52:55] offset:16
	ds_write_b128 v177, v[56:59] offset:32
	ds_write_b128 v177, v[60:63] offset:48
	ds_write_b128 v177, v[32:35] offset:128
	ds_write_b128 v177, v[36:39] offset:144
	ds_write_b128 v177, v[40:43] offset:160
	ds_write_b128 v177, v[44:47] offset:176
	v_lshlrev_b64 v[0:1], 11, v[92:93]
	v_lshl_add_u64 v[2:3], v[206:207], 0, v[0:1]
	v_lshl_add_u64 v[0:1], v[204:205], 0, v[0:1]
	global_load_dwordx4 v[60:63], v[2:3], off nt
	global_load_dwordx4 v[56:59], v[0:1], off nt
	global_load_dword v94, v179, s[12:13] offset:256
	v_lshlrev_b64 v[0:1], 11, v[88:89]
	v_lshl_add_u64 v[2:3], v[206:207], 0, v[0:1]
	v_lshl_add_u64 v[0:1], v[204:205], 0, v[0:1]
	global_load_dwordx4 v[52:55], v[2:3], off nt
	global_load_dwordx4 v[48:51], v[0:1], off nt
	global_load_dword v90, v179, s[12:13] offset:288
	v_lshlrev_b64 v[0:1], 11, v[84:85]
	v_lshl_add_u64 v[2:3], v[206:207], 0, v[0:1]
	v_lshl_add_u64 v[0:1], v[204:205], 0, v[0:1]
	global_load_dwordx4 v[44:47], v[2:3], off nt
	global_load_dwordx4 v[40:43], v[0:1], off nt
	global_load_dword v86, v179, s[12:13] offset:320
	v_lshlrev_b64 v[0:1], 11, v[80:81]
	v_lshl_add_u64 v[2:3], v[206:207], 0, v[0:1]
	v_lshl_add_u64 v[0:1], v[204:205], 0, v[0:1]
	v_mov_b32_e32 v75, s15
	v_or_b32_e32 v74, s14, v184
	global_load_dwordx4 v[36:39], v[2:3], off nt
	global_load_dwordx4 v[32:35], v[0:1], off nt
	global_load_dword v82, v179, s[12:13] offset:352
	v_lshlrev_b64 v[0:1], 11, v[74:75]
	v_lshl_add_u64 v[2:3], v[206:207], 0, v[0:1]
	v_lshl_add_u64 v[0:1], v[204:205], 0, v[0:1]
	v_mov_b32_e32 v71, s15
	v_or_b32_e32 v70, s14, v186
	global_load_dwordx4 v[24:27], v[2:3], off nt
	global_load_dwordx4 v[20:23], v[0:1], off nt
	global_load_dword v76, v179, s[12:13] offset:384
	v_lshlrev_b64 v[0:1], 11, v[70:71]
	v_lshl_add_u64 v[2:3], v[206:207], 0, v[0:1]
	v_lshl_add_u64 v[0:1], v[204:205], 0, v[0:1]
	global_load_dwordx4 v[16:19], v[2:3], off nt
	global_load_dwordx4 v[12:15], v[0:1], off nt
	global_load_dword v72, v179, s[12:13] offset:416
	v_lshlrev_b64 v[0:1], 11, v[66:67]
	v_lshlrev_b64 v[28:29], 11, v[64:65]
	v_lshl_add_u64 v[2:3], v[206:207], 0, v[0:1]
	v_lshl_add_u64 v[0:1], v[204:205], 0, v[0:1]
	v_lshl_add_u64 v[8:9], v[206:207], 0, v[28:29]
	v_lshl_add_u64 v[28:29], v[204:205], 0, v[28:29]
	global_load_dwordx4 v[4:7], v[2:3], off nt
	s_nop 0
	global_load_dwordx4 v[0:3], v[0:1], off nt
	s_nop 0
	global_load_dword v68, v179, s[12:13] offset:448
	s_nop 0
	global_load_dwordx4 v[8:11], v[8:9], off nt
	s_nop 0
	global_load_dwordx4 v[28:31], v[28:29], off nt
	s_nop 0
	global_load_dword v78, v179, s[12:13] offset:480
	s_waitcnt vmcnt(1)
	ds_read_b128 v[96:99], v173
	ds_read_b128 v[100:103], v173 offset:16
	v_lshlrev_b32_e32 v104, 16, v60
	v_and_b32_e32 v105, 0xffff0000, v60
	v_lshlrev_b32_e32 v60, 16, v61
	s_waitcnt lgkmcnt(1)
	v_pk_add_f32 v[96:97], v[94:95], v[96:97] op_sel_hi:[0,1]
	v_pk_mul_f32 v[96:97], v[96:97], v[104:105]
	v_lshlrev_b32_e32 v104, 16, v56
	v_and_b32_e32 v105, 0xffff0000, v56
	v_pk_mul_f32 v[96:97], v[96:97], v[104:105]
	v_and_b32_e32 v61, 0xffff0000, v61
	v_cvt_pk_bf16_f32 v56, v96, v97
	v_pk_add_f32 v[96:97], v[94:95], v[98:99] op_sel_hi:[0,1]
	v_pk_mul_f32 v[60:61], v[96:97], v[60:61]
	v_lshlrev_b32_e32 v96, 16, v57
	v_and_b32_e32 v97, 0xffff0000, v57
	v_pk_mul_f32 v[60:61], v[60:61], v[96:97]
	s_waitcnt lgkmcnt(0)
	v_pk_add_f32 v[96:97], v[94:95], v[100:101] op_sel_hi:[0,1]
	v_cvt_pk_bf16_f32 v57, v60, v61
	v_lshlrev_b32_e32 v60, 16, v62
	v_and_b32_e32 v61, 0xffff0000, v62
	v_pk_mul_f32 v[60:61], v[96:97], v[60:61]
	v_lshlrev_b32_e32 v96, 16, v58
	v_and_b32_e32 v97, 0xffff0000, v58
	v_pk_mul_f32 v[60:61], v[60:61], v[96:97]
	s_nop 0
	v_cvt_pk_bf16_f32 v58, v60, v61
	v_lshlrev_b32_e32 v60, 16, v63
	v_and_b32_e32 v61, 0xffff0000, v63
	v_pk_add_f32 v[62:63], v[94:95], v[102:103] op_sel_hi:[0,1]
	v_pk_mul_f32 v[60:61], v[62:63], v[60:61]
	v_lshlrev_b32_e32 v62, 16, v59
	v_and_b32_e32 v63, 0xffff0000, v59
	v_pk_mul_f32 v[60:61], v[60:61], v[62:63]
	s_nop 0
	v_cvt_pk_bf16_f32 v59, v60, v61
	v_lshlrev_b64 v[60:61], 12, v[92:93]
	v_lshl_add_u64 v[60:61], v[202:203], 0, v[60:61]
	global_store_dwordx4 v[60:61], v[56:59], off
	ds_read_b128 v[56:59], v173 offset:2176
	ds_read_b128 v[60:63], v173 offset:2192
	v_lshlrev_b32_e32 v92, 16, v52
	v_and_b32_e32 v93, 0xffff0000, v52
	v_lshlrev_b32_e32 v52, 16, v53
	s_waitcnt lgkmcnt(1)
	v_pk_add_f32 v[56:57], v[90:91], v[56:57] op_sel_hi:[0,1]
	v_pk_mul_f32 v[56:57], v[56:57], v[92:93]
	v_lshlrev_b32_e32 v92, 16, v48
	v_and_b32_e32 v93, 0xffff0000, v48
	v_pk_mul_f32 v[56:57], v[56:57], v[92:93]
	v_and_b32_e32 v53, 0xffff0000, v53
	v_cvt_pk_bf16_f32 v48, v56, v57
	v_pk_add_f32 v[56:57], v[90:91], v[58:59] op_sel_hi:[0,1]
	v_pk_mul_f32 v[52:53], v[56:57], v[52:53]
	v_lshlrev_b32_e32 v56, 16, v49
	v_and_b32_e32 v57, 0xffff0000, v49
	v_pk_mul_f32 v[52:53], v[52:53], v[56:57]
	s_waitcnt lgkmcnt(0)
	v_pk_add_f32 v[56:57], v[90:91], v[60:61] op_sel_hi:[0,1]
	v_cvt_pk_bf16_f32 v49, v52, v53
	v_lshlrev_b32_e32 v52, 16, v54
	v_and_b32_e32 v53, 0xffff0000, v54
	v_pk_mul_f32 v[52:53], v[56:57], v[52:53]
	v_lshlrev_b32_e32 v56, 16, v50
	v_and_b32_e32 v57, 0xffff0000, v50
	v_pk_mul_f32 v[52:53], v[52:53], v[56:57]
	v_lshlrev_b32_e32 v56, 16, v44
	v_cvt_pk_bf16_f32 v50, v52, v53
	v_lshlrev_b32_e32 v52, 16, v55
	v_and_b32_e32 v53, 0xffff0000, v55
	v_pk_add_f32 v[54:55], v[90:91], v[62:63] op_sel_hi:[0,1]
	v_pk_mul_f32 v[52:53], v[54:55], v[52:53]
	v_lshlrev_b32_e32 v54, 16, v51
	v_and_b32_e32 v55, 0xffff0000, v51
	v_pk_mul_f32 v[52:53], v[52:53], v[54:55]
	v_and_b32_e32 v57, 0xffff0000, v44
	v_cvt_pk_bf16_f32 v51, v52, v53
	v_lshlrev_b64 v[52:53], 12, v[88:89]
	v_lshl_add_u64 v[52:53], v[202:203], 0, v[52:53]
	global_store_dwordx4 v[52:53], v[48:51], off
	ds_read_b128 v[48:51], v173 offset:4352
	ds_read_b128 v[52:55], v173 offset:4368
	v_lshlrev_b32_e32 v44, 16, v45
	v_and_b32_e32 v45, 0xffff0000, v45
	s_waitcnt lgkmcnt(1)
	v_pk_add_f32 v[48:49], v[86:87], v[48:49] op_sel_hi:[0,1]
	v_pk_mul_f32 v[48:49], v[48:49], v[56:57]
	v_lshlrev_b32_e32 v56, 16, v40
	v_and_b32_e32 v57, 0xffff0000, v40
	v_pk_mul_f32 v[48:49], v[48:49], v[56:57]
	s_nop 0
	v_cvt_pk_bf16_f32 v40, v48, v49
	v_pk_add_f32 v[48:49], v[86:87], v[50:51] op_sel_hi:[0,1]
	v_pk_mul_f32 v[44:45], v[48:49], v[44:45]
	v_lshlrev_b32_e32 v48, 16, v41
	v_and_b32_e32 v49, 0xffff0000, v41
	v_pk_mul_f32 v[44:45], v[44:45], v[48:49]
	s_waitcnt lgkmcnt(0)
	v_pk_add_f32 v[48:49], v[86:87], v[52:53] op_sel_hi:[0,1]
	v_cvt_pk_bf16_f32 v41, v44, v45
	v_lshlrev_b32_e32 v44, 16, v46
	v_and_b32_e32 v45, 0xffff0000, v46
	v_pk_mul_f32 v[44:45], v[48:49], v[44:45]
	v_lshlrev_b32_e32 v48, 16, v42
	v_and_b32_e32 v49, 0xffff0000, v42
	v_pk_mul_f32 v[44:45], v[44:45], v[48:49]
	v_lshlrev_b32_e32 v48, 16, v36
	v_cvt_pk_bf16_f32 v42, v44, v45
	v_lshlrev_b32_e32 v44, 16, v47
	v_and_b32_e32 v45, 0xffff0000, v47
	v_pk_add_f32 v[46:47], v[86:87], v[54:55] op_sel_hi:[0,1]
	v_pk_mul_f32 v[44:45], v[46:47], v[44:45]
	v_lshlrev_b32_e32 v46, 16, v43
	v_and_b32_e32 v47, 0xffff0000, v43
	v_pk_mul_f32 v[44:45], v[44:45], v[46:47]
	v_and_b32_e32 v49, 0xffff0000, v36
	v_cvt_pk_bf16_f32 v43, v44, v45
	v_lshlrev_b64 v[44:45], 12, v[84:85]
	v_lshl_add_u64 v[44:45], v[202:203], 0, v[44:45]
	global_store_dwordx4 v[44:45], v[40:43], off
	ds_read_b128 v[40:43], v173 offset:6528
	ds_read_b128 v[44:47], v173 offset:6544
	v_lshlrev_b32_e32 v36, 16, v37
	v_and_b32_e32 v37, 0xffff0000, v37
	s_waitcnt lgkmcnt(1)
	v_pk_add_f32 v[40:41], v[82:83], v[40:41] op_sel_hi:[0,1]
	v_pk_mul_f32 v[40:41], v[40:41], v[48:49]
	v_lshlrev_b32_e32 v48, 16, v32
	v_and_b32_e32 v49, 0xffff0000, v32
	v_pk_mul_f32 v[40:41], v[40:41], v[48:49]
	s_nop 0
	v_cvt_pk_bf16_f32 v32, v40, v41
	v_pk_add_f32 v[40:41], v[82:83], v[42:43] op_sel_hi:[0,1]
	v_pk_mul_f32 v[36:37], v[40:41], v[36:37]
	v_lshlrev_b32_e32 v40, 16, v33
	v_and_b32_e32 v41, 0xffff0000, v33
	v_pk_mul_f32 v[36:37], v[36:37], v[40:41]
	s_waitcnt lgkmcnt(0)
	v_pk_add_f32 v[40:41], v[82:83], v[44:45] op_sel_hi:[0,1]
	v_cvt_pk_bf16_f32 v33, v36, v37
	v_lshlrev_b32_e32 v36, 16, v38
	v_and_b32_e32 v37, 0xffff0000, v38
	v_pk_mul_f32 v[36:37], v[40:41], v[36:37]
	v_lshlrev_b32_e32 v40, 16, v34
	v_and_b32_e32 v41, 0xffff0000, v34
	v_pk_mul_f32 v[36:37], v[36:37], v[40:41]
	v_lshlrev_b32_e32 v40, 16, v24
	v_cvt_pk_bf16_f32 v34, v36, v37
	v_lshlrev_b32_e32 v36, 16, v39
	v_and_b32_e32 v37, 0xffff0000, v39
	v_pk_add_f32 v[38:39], v[82:83], v[46:47] op_sel_hi:[0,1]
	v_pk_mul_f32 v[36:37], v[38:39], v[36:37]
	v_lshlrev_b32_e32 v38, 16, v35
	v_and_b32_e32 v39, 0xffff0000, v35
	v_pk_mul_f32 v[36:37], v[36:37], v[38:39]
	v_and_b32_e32 v41, 0xffff0000, v24
	v_cvt_pk_bf16_f32 v35, v36, v37
	v_lshlrev_b64 v[36:37], 12, v[80:81]
	v_lshl_add_u64 v[36:37], v[202:203], 0, v[36:37]
	global_store_dwordx4 v[36:37], v[32:35], off
	ds_read_b128 v[36:39], v173 offset:8704
	ds_read_b128 v[32:35], v173 offset:8720
	v_lshlrev_b32_e32 v24, 16, v25
	v_and_b32_e32 v25, 0xffff0000, v25
	s_waitcnt lgkmcnt(1)
	v_pk_add_f32 v[36:37], v[76:77], v[36:37] op_sel_hi:[0,1]
	v_pk_mul_f32 v[36:37], v[36:37], v[40:41]
	v_lshlrev_b32_e32 v40, 16, v20
	v_and_b32_e32 v41, 0xffff0000, v20
	v_pk_mul_f32 v[36:37], v[36:37], v[40:41]
	s_waitcnt lgkmcnt(0)
	v_pk_add_f32 v[32:33], v[76:77], v[32:33] op_sel_hi:[0,1]
	v_cvt_pk_bf16_f32 v20, v36, v37
	v_pk_add_f32 v[36:37], v[76:77], v[38:39] op_sel_hi:[0,1]
	v_pk_mul_f32 v[24:25], v[36:37], v[24:25]
	v_lshlrev_b32_e32 v36, 16, v21
	v_and_b32_e32 v37, 0xffff0000, v21
	v_pk_mul_f32 v[24:25], v[24:25], v[36:37]
	s_nop 0
	v_cvt_pk_bf16_f32 v21, v24, v25
	v_lshlrev_b32_e32 v24, 16, v26
	v_and_b32_e32 v25, 0xffff0000, v26
	v_pk_mul_f32 v[24:25], v[32:33], v[24:25]
	v_lshlrev_b32_e32 v32, 16, v22
	v_and_b32_e32 v33, 0xffff0000, v22
	v_pk_mul_f32 v[24:25], v[24:25], v[32:33]
	v_lshlrev_b32_e32 v32, 16, v16
	v_cvt_pk_bf16_f32 v22, v24, v25
	v_lshlrev_b32_e32 v24, 16, v27
	v_and_b32_e32 v25, 0xffff0000, v27
	v_pk_add_f32 v[26:27], v[76:77], v[34:35] op_sel_hi:[0,1]
	v_pk_mul_f32 v[24:25], v[26:27], v[24:25]
	v_lshlrev_b32_e32 v26, 16, v23
	v_and_b32_e32 v27, 0xffff0000, v23
	v_pk_mul_f32 v[24:25], v[24:25], v[26:27]
	v_and_b32_e32 v33, 0xffff0000, v16
	v_cvt_pk_bf16_f32 v23, v24, v25
	v_lshlrev_b64 v[24:25], 12, v[74:75]
	v_lshl_add_u64 v[24:25], v[202:203], 0, v[24:25]
	global_store_dwordx4 v[24:25], v[20:23], off
	ds_read_b128 v[20:23], v173 offset:10880
	ds_read_b128 v[24:27], v173 offset:10896
	v_lshlrev_b32_e32 v16, 16, v17
	v_and_b32_e32 v17, 0xffff0000, v17
	s_waitcnt lgkmcnt(1)
	v_pk_add_f32 v[20:21], v[72:73], v[20:21] op_sel_hi:[0,1]
	v_pk_mul_f32 v[20:21], v[20:21], v[32:33]
	v_lshlrev_b32_e32 v32, 16, v12
	v_and_b32_e32 v33, 0xffff0000, v12
	v_pk_mul_f32 v[20:21], v[20:21], v[32:33]
	s_nop 0
	v_cvt_pk_bf16_f32 v12, v20, v21
	v_pk_add_f32 v[20:21], v[72:73], v[22:23] op_sel_hi:[0,1]
	v_pk_mul_f32 v[16:17], v[20:21], v[16:17]
	v_lshlrev_b32_e32 v20, 16, v13
	v_and_b32_e32 v21, 0xffff0000, v13
	v_pk_mul_f32 v[16:17], v[16:17], v[20:21]
	s_waitcnt lgkmcnt(0)
	v_pk_add_f32 v[20:21], v[72:73], v[24:25] op_sel_hi:[0,1]
	v_cvt_pk_bf16_f32 v13, v16, v17
	v_lshlrev_b32_e32 v16, 16, v18
	v_and_b32_e32 v17, 0xffff0000, v18
	v_pk_mul_f32 v[16:17], v[20:21], v[16:17]
	v_lshlrev_b32_e32 v20, 16, v14
	v_and_b32_e32 v21, 0xffff0000, v14
	v_pk_mul_f32 v[16:17], v[16:17], v[20:21]
	v_lshlrev_b32_e32 v20, 16, v4
	v_cvt_pk_bf16_f32 v14, v16, v17
	v_lshlrev_b32_e32 v16, 16, v19
	v_and_b32_e32 v17, 0xffff0000, v19
	v_pk_add_f32 v[18:19], v[72:73], v[26:27] op_sel_hi:[0,1]
	v_pk_mul_f32 v[16:17], v[18:19], v[16:17]
	v_lshlrev_b32_e32 v18, 16, v15
	v_and_b32_e32 v19, 0xffff0000, v15
	v_pk_mul_f32 v[16:17], v[16:17], v[18:19]
	v_and_b32_e32 v21, 0xffff0000, v4
	v_cvt_pk_bf16_f32 v15, v16, v17
	v_lshlrev_b64 v[16:17], 12, v[70:71]
	v_lshl_add_u64 v[16:17], v[202:203], 0, v[16:17]
	global_store_dwordx4 v[16:17], v[12:15], off
	ds_read_b128 v[12:15], v173 offset:13056
	ds_read_b128 v[16:19], v173 offset:13072
	v_lshlrev_b32_e32 v4, 16, v5
	v_and_b32_e32 v5, 0xffff0000, v5
	s_waitcnt lgkmcnt(1)
	v_pk_add_f32 v[12:13], v[68:69], v[12:13] op_sel_hi:[0,1]
	v_pk_mul_f32 v[12:13], v[12:13], v[20:21]
	v_lshlrev_b32_e32 v20, 16, v0
	v_and_b32_e32 v21, 0xffff0000, v0
	v_pk_mul_f32 v[12:13], v[12:13], v[20:21]
	s_nop 0
	v_cvt_pk_bf16_f32 v0, v12, v13
	v_pk_add_f32 v[12:13], v[68:69], v[14:15] op_sel_hi:[0,1]
	v_pk_mul_f32 v[4:5], v[12:13], v[4:5]
	v_lshlrev_b32_e32 v12, 16, v1
	v_and_b32_e32 v13, 0xffff0000, v1
	v_pk_mul_f32 v[4:5], v[4:5], v[12:13]
	s_waitcnt lgkmcnt(0)
	v_pk_add_f32 v[12:13], v[68:69], v[16:17] op_sel_hi:[0,1]
	v_cvt_pk_bf16_f32 v1, v4, v5
	v_lshlrev_b32_e32 v4, 16, v6
	v_and_b32_e32 v5, 0xffff0000, v6
	v_pk_mul_f32 v[4:5], v[12:13], v[4:5]
	v_lshlrev_b32_e32 v12, 16, v2
	v_and_b32_e32 v13, 0xffff0000, v2
	v_pk_mul_f32 v[4:5], v[4:5], v[12:13]
	v_lshlrev_b32_e32 v12, 16, v8
	v_cvt_pk_bf16_f32 v2, v4, v5
	v_lshlrev_b32_e32 v4, 16, v7
	v_and_b32_e32 v5, 0xffff0000, v7
	v_pk_add_f32 v[6:7], v[68:69], v[18:19] op_sel_hi:[0,1]
	v_pk_mul_f32 v[4:5], v[6:7], v[4:5]
	v_lshlrev_b32_e32 v6, 16, v3
	v_and_b32_e32 v7, 0xffff0000, v3
	v_pk_mul_f32 v[4:5], v[4:5], v[6:7]
	v_and_b32_e32 v13, 0xffff0000, v8
	v_cvt_pk_bf16_f32 v3, v4, v5
	v_lshlrev_b64 v[4:5], 12, v[66:67]
	v_lshl_add_u64 v[4:5], v[202:203], 0, v[4:5]
	global_store_dwordx4 v[4:5], v[0:3], off
	ds_read_b128 v[0:3], v173 offset:15232
	ds_read_b128 v[4:7], v173 offset:15248
	v_lshlrev_b32_e32 v8, 16, v9
	v_and_b32_e32 v9, 0xffff0000, v9
	s_waitcnt vmcnt(7) lgkmcnt(1)
	v_pk_add_f32 v[0:1], v[78:79], v[0:1] op_sel_hi:[0,1]
	v_pk_add_f32 v[2:3], v[78:79], v[2:3] op_sel_hi:[0,1]
	v_pk_mul_f32 v[0:1], v[0:1], v[12:13]
	v_lshlrev_b32_e32 v12, 16, v28
	v_and_b32_e32 v13, 0xffff0000, v28
	v_pk_mul_f32 v[2:3], v[2:3], v[8:9]
	v_lshlrev_b32_e32 v8, 16, v29
	v_and_b32_e32 v9, 0xffff0000, v29
	v_pk_mul_f32 v[0:1], v[0:1], v[12:13]
	v_pk_mul_f32 v[2:3], v[2:3], v[8:9]
	v_cvt_pk_bf16_f32 v0, v0, v1
	v_cvt_pk_bf16_f32 v1, v2, v3
	v_lshlrev_b32_e32 v2, 16, v10
	v_and_b32_e32 v3, 0xffff0000, v10
	s_waitcnt lgkmcnt(0)
	v_pk_add_f32 v[4:5], v[78:79], v[4:5] op_sel_hi:[0,1]
	v_pk_mul_f32 v[2:3], v[4:5], v[2:3]
	v_lshlrev_b32_e32 v4, 16, v30
	v_and_b32_e32 v5, 0xffff0000, v30
	v_pk_mul_f32 v[2:3], v[2:3], v[4:5]
	v_lshlrev_b32_e32 v4, 16, v11
	v_and_b32_e32 v5, 0xffff0000, v11
	v_pk_add_f32 v[6:7], v[78:79], v[6:7] op_sel_hi:[0,1]
	v_pk_mul_f32 v[4:5], v[6:7], v[4:5]
	v_lshlrev_b32_e32 v6, 16, v31
	v_and_b32_e32 v7, 0xffff0000, v31
	v_pk_mul_f32 v[4:5], v[4:5], v[6:7]
	v_cvt_pk_bf16_f32 v2, v2, v3
	v_cvt_pk_bf16_f32 v3, v4, v5
	v_lshlrev_b64 v[4:5], 12, v[64:65]
	v_lshl_add_u64 v[4:5], v[202:203], 0, v[4:5]
	global_store_dwordx4 v[4:5], v[0:3], off
	s_cbranch_scc1 .LBB0_124
	v_readlane_b32 s44, v253, 42
	v_readlane_b32 s29, v253, 41
	v_readlane_b32 s45, v253, 43
	v_readlane_b32 s37, v253, 46
	s_mov_b32 s46, s27
